# static priority raise (s_setprio 2) for the prompt-scan compute waves over the chunk loop
# speedup vs baseline: 1.0104x; 1.0104x over previous
; #define SCAN_BAR() asm volatile("s_barrier" ::: "memory")
; __device__ __forceinline__ void scan_unit(const Ctx& C0, const float* scn, int T, int quarter, const float* S0, float* Sout, unsigned char* obase, int mode) {
;     ...
;         float S0x = 0.f, S1x = 0.f, S2x = 0.f, S3x = 0.f;
;         if (S0) { const f32x4 t = *(const f32x4*)(S0 + irow * 64 + 4 * q); S0x = t.x; S1x = t.y; S2x = t.z; S3x = t.w; }
;         SCAN_BAR();
;         for (int k = 0; k < nch; ++k) {
;             const unsigned aq = (unsigned)(size_t)(C.lds + (k & 1) * SLOT_B) + 16u * (unsigned)q, av = (unsigned)(size_t)(C.lds + (k & 1) * SLOT_B) + (320u + (unsigned)irow) * 4u;
;             float osel0, osel1;
;             asm volatile(SCAN_CHUNK_ASM : "+v"(S0x), "+v"(S1x), "+v"(S2x), "+v"(S3x), "=&v"(osel0), "=&v"(osel1) : "v"(aq), "v"(av), "v"(q) : SCAN_CHUNK_CLOBBERS, "memory");
.LBB0_683:
	s_and_b64 vcc, exec, s[0:1]
	s_cbranch_vccz .LBB0_687
	v_lshrrev_b32_e32 v2, 4, v53
	s_lshl_b32 s1, s9, 2
	s_bfe_u32 s0, s72, 0x20003
	v_and_or_b32 v0, s1, 12, v2
	v_lshl_or_b32 v0, s0, 4, v0
	s_lshl_b32 s10, s2, 8
	s_lshl_b32 s0, s0, 6
	s_mul_i32 s9, s3, 0x5600000
	v_mov_b32_e32 v5, 0x500
	s_or_b32 s0, s10, s0
	s_mul_hi_i32 s1, s3, 0x5600000
	v_lshl_or_b32 v6, v0, 2, v5
	s_add_i32 s11, 0, 0xc000
	s_or_b32 s0, s9, s0
	s_waitcnt lgkmcnt(0)
	v_and_b32_e32 v3, 15, v52
	v_add_u32_e32 v9, 0, v6
	v_add_u32_e32 v11, s11, v6
	v_mov_b32_e32 v6, s0
	v_mov_b32_e32 v7, s1
	s_movk_i32 s0, 0x2b00
	v_mad_u64_u32 v[6:7], s[0:1], v3, s0, v[6:7]
	s_lshr_b32 s0, s8, 2
	s_and_b32 s0, s0, 48
	v_lshlrev_b32_e32 v2, 2, v2
	s_barrier
	v_or3_b32 v6, s0, v2, v6
	v_readlane_b32 s0, v253, 4
	v_lshlrev_b32_e32 v4, 4, v3
	v_readlane_b32 s1, v253, 5
	v_add_u32_e32 v5, 0, v4
	v_add_u32_e32 v10, s11, v4
	v_lshl_add_u64 v[6:7], s[0:1], 0, v[6:7]
	v_mov_b32_e32 v8, 0
	s_mov_b64 s[0:1], 0
	v_mov_b32_e32 v12, 0
	v_mov_b32_e32 v13, 0
	v_mov_b32_e32 v2, 0
	v_mov_b32_e32 v138, v2
	v_mov_b32_e32 v139, v13
	v_mov_b32_e32 v140, v12
	v_mov_b32_e32 v141, v8
	s_setprio 2
.LBB0_685:
	ds_read_b128 v[164:167], v5 offset:0
	ds_read_b128 v[168:171], v5 offset:256
	ds_read_b128 v[172:175], v5 offset:512
	ds_read_b128 v[176:179], v5 offset:768
	ds_read_b128 v[180:183], v5 offset:1024
	ds_read_b32 v184, v9 offset:0
	ds_read_b128 v[186:189], v5 offset:1536
	ds_read_b128 v[190:193], v5 offset:1792
	ds_read_b128 v[194:197], v5 offset:2048
	ds_read_b128 v[198:201], v5 offset:2304
	ds_read_b128 v[202:205], v5 offset:2560
	ds_read_b32 v206, v9 offset:1536
	s_waitcnt lgkmcnt(6)
	v_pk_mul_f32 v[144:145], v[138:139], v[164:165]
	v_pk_fma_f32 v[144:145], v[140:141], v[166:167], v[144:145]
	v_add_f32 v146, v144, v145
	ds_read_b128 v[208:211], v5 offset:3072
	ds_read_b128 v[212:215], v5 offset:3328
	ds_read_b128 v[216:219], v5 offset:3584
	ds_read_b128 v[220:223], v5 offset:3840
	ds_read_b128 v[224:227], v5 offset:4096
	ds_read_b32 v228, v9 offset:3072
	v_add_f32_dpp v146, v146, v146 quad_perm:[1,0,3,2] row_mask:0xf bank_mask:0xf bound_ctrl:1
	s_nop 0
	s_nop 0
	v_add_f32_dpp v146, v146, v146 quad_perm:[2,3,0,1] row_mask:0xf bank_mask:0xf bound_ctrl:1
	s_nop 0
	v_pk_mul_f32 v[176:177], v[176:177], v[184:185] op_sel_hi:[1,0]
	v_add_f32_dpp v146, v146, v146 row_half_mirror row_mask:0xf bank_mask:0xf bound_ctrl:1
	v_pk_mul_f32 v[178:179], v[178:179], v[184:185] op_sel_hi:[1,0]
	s_waitcnt lgkmcnt(6)
	v_add_f32_dpp v146, v146, v146 row_mirror row_mask:0xf bank_mask:0xf bound_ctrl:1
	v_pk_fma_f32 v[176:177], v[146:147], v[168:169], v[176:177] op_sel_hi:[0,1,1] neg_lo:[1,0,0] neg_hi:[1,0,0]
	v_pk_fma_f32 v[178:179], v[146:147], v[170:171], v[178:179] op_sel_hi:[0,1,1] neg_lo:[1,0,0] neg_hi:[1,0,0]
	v_pk_fma_f32 v[138:139], v[138:139], v[172:173], v[176:177]
	v_pk_fma_f32 v[140:141], v[140:141], v[174:175], v[178:179]
	v_pk_mul_f32 v[144:145], v[138:139], v[186:187]
	v_pk_fma_f32 v[144:145], v[140:141], v[188:189], v[144:145]
	v_add_f32 v146, v144, v145
	ds_read_b128 v[230:233], v5 offset:4608
	ds_read_b128 v[234:237], v5 offset:4864
	ds_read_b128 v[238:241], v5 offset:5120
	ds_read_b128 v[242:245], v5 offset:5376
	ds_read_b128 v[246:249], v5 offset:5632
	ds_read_b32 v250, v9 offset:4608
	v_add_f32_dpp v146, v146, v146 quad_perm:[1,0,3,2] row_mask:0xf bank_mask:0xf bound_ctrl:1
	v_pk_mul_f32 v[180:181], v[138:139], v[180:181]
	v_pk_fma_f32 v[180:181], v[140:141], v[182:183], v[180:181]
	v_add_f32_dpp v146, v146, v146 quad_perm:[2,3,0,1] row_mask:0xf bank_mask:0xf bound_ctrl:1
	v_add_f32 v148, v180, v181
	v_pk_mul_f32 v[198:199], v[198:199], v[206:207] op_sel_hi:[1,0]
	v_add_f32_dpp v146, v146, v146 row_half_mirror row_mask:0xf bank_mask:0xf bound_ctrl:1
	v_pk_mul_f32 v[200:201], v[200:201], v[206:207] op_sel_hi:[1,0]
	s_waitcnt lgkmcnt(6)
	v_add_f32_dpp v146, v146, v146 row_mirror row_mask:0xf bank_mask:0xf bound_ctrl:1
	v_pk_fma_f32 v[198:199], v[146:147], v[190:191], v[198:199] op_sel_hi:[0,1,1] neg_lo:[1,0,0] neg_hi:[1,0,0]
	v_pk_fma_f32 v[200:201], v[146:147], v[192:193], v[200:201] op_sel_hi:[0,1,1] neg_lo:[1,0,0] neg_hi:[1,0,0]
	v_pk_fma_f32 v[138:139], v[138:139], v[194:195], v[198:199]
	v_pk_fma_f32 v[140:141], v[140:141], v[196:197], v[200:201]
	v_pk_mul_f32 v[144:145], v[138:139], v[208:209]
	v_pk_fma_f32 v[144:145], v[140:141], v[210:211], v[144:145]
	v_add_f32 v146, v144, v145
	ds_read_b128 v[164:167], v5 offset:6144
	ds_read_b128 v[168:171], v5 offset:6400
	ds_read_b128 v[172:175], v5 offset:6656
	ds_read_b128 v[176:179], v5 offset:6912
	ds_read_b128 v[180:183], v5 offset:7168
	ds_read_b32 v184, v9 offset:6144
	v_add_f32_dpp v146, v146, v146 quad_perm:[1,0,3,2] row_mask:0xf bank_mask:0xf bound_ctrl:1
	v_pk_mul_f32 v[202:203], v[138:139], v[202:203]
	v_pk_fma_f32 v[202:203], v[140:141], v[204:205], v[202:203]
	v_add_f32_dpp v146, v146, v146 quad_perm:[2,3,0,1] row_mask:0xf bank_mask:0xf bound_ctrl:1
	v_add_f32 v149, v202, v203
	v_pk_mul_f32 v[220:221], v[220:221], v[228:229] op_sel_hi:[1,0]
	v_add_f32_dpp v146, v146, v146 row_half_mirror row_mask:0xf bank_mask:0xf bound_ctrl:1
	v_pk_mul_f32 v[222:223], v[222:223], v[228:229] op_sel_hi:[1,0]
	s_waitcnt lgkmcnt(6)
	v_add_f32_dpp v146, v146, v146 row_mirror row_mask:0xf bank_mask:0xf bound_ctrl:1
	v_pk_fma_f32 v[220:221], v[146:147], v[212:213], v[220:221] op_sel_hi:[0,1,1] neg_lo:[1,0,0] neg_hi:[1,0,0]
	v_pk_fma_f32 v[222:223], v[146:147], v[214:215], v[222:223] op_sel_hi:[0,1,1] neg_lo:[1,0,0] neg_hi:[1,0,0]
	v_pk_fma_f32 v[138:139], v[138:139], v[216:217], v[220:221]
	v_pk_fma_f32 v[140:141], v[140:141], v[218:219], v[222:223]
	v_pk_mul_f32 v[144:145], v[138:139], v[230:231]
	v_pk_fma_f32 v[144:145], v[140:141], v[232:233], v[144:145]
	v_add_f32 v146, v144, v145
	ds_read_b128 v[186:189], v5 offset:7680
	ds_read_b128 v[190:193], v5 offset:7936
	ds_read_b128 v[194:197], v5 offset:8192
	ds_read_b128 v[198:201], v5 offset:8448
	ds_read_b128 v[202:205], v5 offset:8704
	ds_read_b32 v206, v9 offset:7680
	v_add_f32_dpp v146, v146, v146 quad_perm:[1,0,3,2] row_mask:0xf bank_mask:0xf bound_ctrl:1
	v_pk_mul_f32 v[224:225], v[138:139], v[224:225]
	v_pk_fma_f32 v[224:225], v[140:141], v[226:227], v[224:225]
	v_add_f32_dpp v146, v146, v146 quad_perm:[2,3,0,1] row_mask:0xf bank_mask:0xf bound_ctrl:1
	v_add_f32 v150, v224, v225
	v_pk_mul_f32 v[242:243], v[242:243], v[250:251] op_sel_hi:[1,0]
	v_add_f32_dpp v146, v146, v146 row_half_mirror row_mask:0xf bank_mask:0xf bound_ctrl:1
	v_pk_mul_f32 v[244:245], v[244:245], v[250:251] op_sel_hi:[1,0]
	s_waitcnt lgkmcnt(6)
	v_add_f32_dpp v146, v146, v146 row_mirror row_mask:0xf bank_mask:0xf bound_ctrl:1
	v_pk_fma_f32 v[242:243], v[146:147], v[234:235], v[242:243] op_sel_hi:[0,1,1] neg_lo:[1,0,0] neg_hi:[1,0,0]
	v_pk_fma_f32 v[244:245], v[146:147], v[236:237], v[244:245] op_sel_hi:[0,1,1] neg_lo:[1,0,0] neg_hi:[1,0,0]
	v_pk_fma_f32 v[138:139], v[138:139], v[238:239], v[242:243]
	v_pk_fma_f32 v[140:141], v[140:141], v[240:241], v[244:245]
	v_pk_mul_f32 v[144:145], v[138:139], v[164:165]
	v_pk_fma_f32 v[144:145], v[140:141], v[166:167], v[144:145]
	v_add_f32 v146, v144, v145
	ds_read_b128 v[208:211], v5 offset:9216
	ds_read_b128 v[212:215], v5 offset:9472
	ds_read_b128 v[216:219], v5 offset:9728
	ds_read_b128 v[220:223], v5 offset:9984
	ds_read_b128 v[224:227], v5 offset:10240
	ds_read_b32 v228, v9 offset:9216
	v_add_f32_dpp v146, v146, v146 quad_perm:[1,0,3,2] row_mask:0xf bank_mask:0xf bound_ctrl:1
	v_pk_mul_f32 v[246:247], v[138:139], v[246:247]
	v_pk_fma_f32 v[246:247], v[140:141], v[248:249], v[246:247]
	v_add_f32_dpp v146, v146, v146 quad_perm:[2,3,0,1] row_mask:0xf bank_mask:0xf bound_ctrl:1
	v_add_f32 v151, v246, v247
	v_pk_mul_f32 v[176:177], v[176:177], v[184:185] op_sel_hi:[1,0]
	v_add_f32_dpp v146, v146, v146 row_half_mirror row_mask:0xf bank_mask:0xf bound_ctrl:1
	v_pk_mul_f32 v[178:179], v[178:179], v[184:185] op_sel_hi:[1,0]
	s_waitcnt lgkmcnt(6)
	v_add_f32_dpp v146, v146, v146 row_mirror row_mask:0xf bank_mask:0xf bound_ctrl:1
	v_pk_fma_f32 v[176:177], v[146:147], v[168:169], v[176:177] op_sel_hi:[0,1,1] neg_lo:[1,0,0] neg_hi:[1,0,0]
	v_pk_fma_f32 v[178:179], v[146:147], v[170:171], v[178:179] op_sel_hi:[0,1,1] neg_lo:[1,0,0] neg_hi:[1,0,0]
	v_pk_fma_f32 v[138:139], v[138:139], v[172:173], v[176:177]
	v_pk_fma_f32 v[140:141], v[140:141], v[174:175], v[178:179]
	v_pk_mul_f32 v[144:145], v[138:139], v[186:187]
	v_pk_fma_f32 v[144:145], v[140:141], v[188:189], v[144:145]
	v_add_f32 v146, v144, v145
	ds_read_b128 v[230:233], v5 offset:10752
	ds_read_b128 v[234:237], v5 offset:11008
	ds_read_b128 v[238:241], v5 offset:11264
	ds_read_b128 v[242:245], v5 offset:11520
	ds_read_b128 v[246:249], v5 offset:11776
	ds_read_b32 v250, v9 offset:10752
	v_add_f32_dpp v146, v146, v146 quad_perm:[1,0,3,2] row_mask:0xf bank_mask:0xf bound_ctrl:1
	v_pk_mul_f32 v[180:181], v[138:139], v[180:181]
	v_pk_fma_f32 v[180:181], v[140:141], v[182:183], v[180:181]
	v_add_f32_dpp v146, v146, v146 quad_perm:[2,3,0,1] row_mask:0xf bank_mask:0xf bound_ctrl:1
	v_add_f32 v152, v180, v181
	v_pk_mul_f32 v[198:199], v[198:199], v[206:207] op_sel_hi:[1,0]
	v_add_f32_dpp v146, v146, v146 row_half_mirror row_mask:0xf bank_mask:0xf bound_ctrl:1
	v_pk_mul_f32 v[200:201], v[200:201], v[206:207] op_sel_hi:[1,0]
	s_waitcnt lgkmcnt(6)
	v_add_f32_dpp v146, v146, v146 row_mirror row_mask:0xf bank_mask:0xf bound_ctrl:1
	v_pk_fma_f32 v[198:199], v[146:147], v[190:191], v[198:199] op_sel_hi:[0,1,1] neg_lo:[1,0,0] neg_hi:[1,0,0]
	v_pk_fma_f32 v[200:201], v[146:147], v[192:193], v[200:201] op_sel_hi:[0,1,1] neg_lo:[1,0,0] neg_hi:[1,0,0]
	v_pk_fma_f32 v[138:139], v[138:139], v[194:195], v[198:199]
	v_pk_fma_f32 v[140:141], v[140:141], v[196:197], v[200:201]
	v_pk_mul_f32 v[144:145], v[138:139], v[208:209]
	v_pk_fma_f32 v[144:145], v[140:141], v[210:211], v[144:145]
	v_add_f32 v146, v144, v145
	ds_read_b128 v[164:167], v5 offset:12288
	ds_read_b128 v[168:171], v5 offset:12544
	ds_read_b128 v[172:175], v5 offset:12800
	ds_read_b128 v[176:179], v5 offset:13056
	ds_read_b128 v[180:183], v5 offset:13312
	ds_read_b32 v184, v9 offset:12288
	v_add_f32_dpp v146, v146, v146 quad_perm:[1,0,3,2] row_mask:0xf bank_mask:0xf bound_ctrl:1
	v_pk_mul_f32 v[202:203], v[138:139], v[202:203]
	v_pk_fma_f32 v[202:203], v[140:141], v[204:205], v[202:203]
	v_add_f32_dpp v146, v146, v146 quad_perm:[2,3,0,1] row_mask:0xf bank_mask:0xf bound_ctrl:1
	v_add_f32 v153, v202, v203
	v_pk_mul_f32 v[220:221], v[220:221], v[228:229] op_sel_hi:[1,0]
	v_add_f32_dpp v146, v146, v146 row_half_mirror row_mask:0xf bank_mask:0xf bound_ctrl:1
	v_pk_mul_f32 v[222:223], v[222:223], v[228:229] op_sel_hi:[1,0]
	s_waitcnt lgkmcnt(6)
	v_add_f32_dpp v146, v146, v146 row_mirror row_mask:0xf bank_mask:0xf bound_ctrl:1
	v_pk_fma_f32 v[220:221], v[146:147], v[212:213], v[220:221] op_sel_hi:[0,1,1] neg_lo:[1,0,0] neg_hi:[1,0,0]
	v_pk_fma_f32 v[222:223], v[146:147], v[214:215], v[222:223] op_sel_hi:[0,1,1] neg_lo:[1,0,0] neg_hi:[1,0,0]
	v_pk_fma_f32 v[138:139], v[138:139], v[216:217], v[220:221]
	v_pk_fma_f32 v[140:141], v[140:141], v[218:219], v[222:223]
	v_pk_mul_f32 v[144:145], v[138:139], v[230:231]
	v_pk_fma_f32 v[144:145], v[140:141], v[232:233], v[144:145]
	v_add_f32 v146, v144, v145
	ds_read_b128 v[186:189], v5 offset:13824
	ds_read_b128 v[190:193], v5 offset:14080
	ds_read_b128 v[194:197], v5 offset:14336
	ds_read_b128 v[198:201], v5 offset:14592
	ds_read_b128 v[202:205], v5 offset:14848
	ds_read_b32 v206, v9 offset:13824
	v_add_f32_dpp v146, v146, v146 quad_perm:[1,0,3,2] row_mask:0xf bank_mask:0xf bound_ctrl:1
	v_pk_mul_f32 v[224:225], v[138:139], v[224:225]
	v_pk_fma_f32 v[224:225], v[140:141], v[226:227], v[224:225]
	v_add_f32_dpp v146, v146, v146 quad_perm:[2,3,0,1] row_mask:0xf bank_mask:0xf bound_ctrl:1
	v_add_f32 v154, v224, v225
	v_pk_mul_f32 v[242:243], v[242:243], v[250:251] op_sel_hi:[1,0]
	v_add_f32_dpp v146, v146, v146 row_half_mirror row_mask:0xf bank_mask:0xf bound_ctrl:1
	v_pk_mul_f32 v[244:245], v[244:245], v[250:251] op_sel_hi:[1,0]
	s_waitcnt lgkmcnt(6)
	v_add_f32_dpp v146, v146, v146 row_mirror row_mask:0xf bank_mask:0xf bound_ctrl:1
	v_pk_fma_f32 v[242:243], v[146:147], v[234:235], v[242:243] op_sel_hi:[0,1,1] neg_lo:[1,0,0] neg_hi:[1,0,0]
	v_pk_fma_f32 v[244:245], v[146:147], v[236:237], v[244:245] op_sel_hi:[0,1,1] neg_lo:[1,0,0] neg_hi:[1,0,0]
	v_pk_fma_f32 v[138:139], v[138:139], v[238:239], v[242:243]
	v_pk_fma_f32 v[140:141], v[140:141], v[240:241], v[244:245]
	v_pk_mul_f32 v[144:145], v[138:139], v[164:165]
	v_pk_fma_f32 v[144:145], v[140:141], v[166:167], v[144:145]
	v_add_f32 v146, v144, v145
	ds_read_b128 v[208:211], v5 offset:15360
	ds_read_b128 v[212:215], v5 offset:15616
	ds_read_b128 v[216:219], v5 offset:15872
	ds_read_b128 v[220:223], v5 offset:16128
	ds_read_b128 v[224:227], v5 offset:16384
	ds_read_b32 v228, v9 offset:15360
	v_add_f32_dpp v146, v146, v146 quad_perm:[1,0,3,2] row_mask:0xf bank_mask:0xf bound_ctrl:1
	v_pk_mul_f32 v[246:247], v[138:139], v[246:247]
	v_pk_fma_f32 v[246:247], v[140:141], v[248:249], v[246:247]
	v_add_f32_dpp v146, v146, v146 quad_perm:[2,3,0,1] row_mask:0xf bank_mask:0xf bound_ctrl:1
	v_add_f32 v155, v246, v247
	v_pk_mul_f32 v[176:177], v[176:177], v[184:185] op_sel_hi:[1,0]
	v_add_f32_dpp v146, v146, v146 row_half_mirror row_mask:0xf bank_mask:0xf bound_ctrl:1
	v_pk_mul_f32 v[178:179], v[178:179], v[184:185] op_sel_hi:[1,0]
	s_waitcnt lgkmcnt(6)
	v_add_f32_dpp v146, v146, v146 row_mirror row_mask:0xf bank_mask:0xf bound_ctrl:1
	v_pk_fma_f32 v[176:177], v[146:147], v[168:169], v[176:177] op_sel_hi:[0,1,1] neg_lo:[1,0,0] neg_hi:[1,0,0]
	v_pk_fma_f32 v[178:179], v[146:147], v[170:171], v[178:179] op_sel_hi:[0,1,1] neg_lo:[1,0,0] neg_hi:[1,0,0]
	v_pk_fma_f32 v[138:139], v[138:139], v[172:173], v[176:177]
	v_pk_fma_f32 v[140:141], v[140:141], v[174:175], v[178:179]
	v_pk_mul_f32 v[144:145], v[138:139], v[186:187]
	v_pk_fma_f32 v[144:145], v[140:141], v[188:189], v[144:145]
	v_add_f32 v146, v144, v145
	ds_read_b128 v[230:233], v5 offset:16896
	ds_read_b128 v[234:237], v5 offset:17152
	ds_read_b128 v[238:241], v5 offset:17408
	ds_read_b128 v[242:245], v5 offset:17664
	ds_read_b128 v[246:249], v5 offset:17920
	ds_read_b32 v250, v9 offset:16896
	v_add_f32_dpp v146, v146, v146 quad_perm:[1,0,3,2] row_mask:0xf bank_mask:0xf bound_ctrl:1
	v_pk_mul_f32 v[180:181], v[138:139], v[180:181]
	v_pk_fma_f32 v[180:181], v[140:141], v[182:183], v[180:181]
	v_add_f32_dpp v146, v146, v146 quad_perm:[2,3,0,1] row_mask:0xf bank_mask:0xf bound_ctrl:1
	v_add_f32 v156, v180, v181
	v_pk_mul_f32 v[198:199], v[198:199], v[206:207] op_sel_hi:[1,0]
	v_add_f32_dpp v146, v146, v146 row_half_mirror row_mask:0xf bank_mask:0xf bound_ctrl:1
	v_pk_mul_f32 v[200:201], v[200:201], v[206:207] op_sel_hi:[1,0]
	s_waitcnt lgkmcnt(6)
	v_add_f32_dpp v146, v146, v146 row_mirror row_mask:0xf bank_mask:0xf bound_ctrl:1
	v_pk_fma_f32 v[198:199], v[146:147], v[190:191], v[198:199] op_sel_hi:[0,1,1] neg_lo:[1,0,0] neg_hi:[1,0,0]
	v_pk_fma_f32 v[200:201], v[146:147], v[192:193], v[200:201] op_sel_hi:[0,1,1] neg_lo:[1,0,0] neg_hi:[1,0,0]
	v_pk_fma_f32 v[138:139], v[138:139], v[194:195], v[198:199]
	v_pk_fma_f32 v[140:141], v[140:141], v[196:197], v[200:201]
	v_pk_mul_f32 v[144:145], v[138:139], v[208:209]
	v_pk_fma_f32 v[144:145], v[140:141], v[210:211], v[144:145]
	v_add_f32 v146, v144, v145
	ds_read_b128 v[164:167], v5 offset:18432
	ds_read_b128 v[168:171], v5 offset:18688
	ds_read_b128 v[172:175], v5 offset:18944
	ds_read_b128 v[176:179], v5 offset:19200
	ds_read_b128 v[180:183], v5 offset:19456
	ds_read_b32 v184, v9 offset:18432
	v_add_f32_dpp v146, v146, v146 quad_perm:[1,0,3,2] row_mask:0xf bank_mask:0xf bound_ctrl:1
	v_pk_mul_f32 v[202:203], v[138:139], v[202:203]
	v_pk_fma_f32 v[202:203], v[140:141], v[204:205], v[202:203]
	v_add_f32_dpp v146, v146, v146 quad_perm:[2,3,0,1] row_mask:0xf bank_mask:0xf bound_ctrl:1
	v_add_f32 v157, v202, v203
	v_pk_mul_f32 v[220:221], v[220:221], v[228:229] op_sel_hi:[1,0]
	v_add_f32_dpp v146, v146, v146 row_half_mirror row_mask:0xf bank_mask:0xf bound_ctrl:1
	v_pk_mul_f32 v[222:223], v[222:223], v[228:229] op_sel_hi:[1,0]
	s_waitcnt lgkmcnt(6)
	v_add_f32_dpp v146, v146, v146 row_mirror row_mask:0xf bank_mask:0xf bound_ctrl:1
	v_pk_fma_f32 v[220:221], v[146:147], v[212:213], v[220:221] op_sel_hi:[0,1,1] neg_lo:[1,0,0] neg_hi:[1,0,0]
	v_pk_fma_f32 v[222:223], v[146:147], v[214:215], v[222:223] op_sel_hi:[0,1,1] neg_lo:[1,0,0] neg_hi:[1,0,0]
	v_pk_fma_f32 v[138:139], v[138:139], v[216:217], v[220:221]
	v_pk_fma_f32 v[140:141], v[140:141], v[218:219], v[222:223]
	v_pk_mul_f32 v[144:145], v[138:139], v[230:231]
	v_pk_fma_f32 v[144:145], v[140:141], v[232:233], v[144:145]
	v_add_f32 v146, v144, v145
	ds_read_b128 v[186:189], v5 offset:19968
	ds_read_b128 v[190:193], v5 offset:20224
	ds_read_b128 v[194:197], v5 offset:20480
	ds_read_b128 v[198:201], v5 offset:20736
	ds_read_b128 v[202:205], v5 offset:20992
	ds_read_b32 v206, v9 offset:19968
	v_add_f32_dpp v146, v146, v146 quad_perm:[1,0,3,2] row_mask:0xf bank_mask:0xf bound_ctrl:1
	v_pk_mul_f32 v[224:225], v[138:139], v[224:225]
	v_pk_fma_f32 v[224:225], v[140:141], v[226:227], v[224:225]
	v_add_f32_dpp v146, v146, v146 quad_perm:[2,3,0,1] row_mask:0xf bank_mask:0xf bound_ctrl:1
	v_add_f32 v158, v224, v225
	v_pk_mul_f32 v[242:243], v[242:243], v[250:251] op_sel_hi:[1,0]
	v_add_f32_dpp v146, v146, v146 row_half_mirror row_mask:0xf bank_mask:0xf bound_ctrl:1
	v_pk_mul_f32 v[244:245], v[244:245], v[250:251] op_sel_hi:[1,0]
	s_waitcnt lgkmcnt(6)
	v_add_f32_dpp v146, v146, v146 row_mirror row_mask:0xf bank_mask:0xf bound_ctrl:1
	v_pk_fma_f32 v[242:243], v[146:147], v[234:235], v[242:243] op_sel_hi:[0,1,1] neg_lo:[1,0,0] neg_hi:[1,0,0]
	v_pk_fma_f32 v[244:245], v[146:147], v[236:237], v[244:245] op_sel_hi:[0,1,1] neg_lo:[1,0,0] neg_hi:[1,0,0]
	v_pk_fma_f32 v[138:139], v[138:139], v[238:239], v[242:243]
	v_pk_fma_f32 v[140:141], v[140:141], v[240:241], v[244:245]
	v_pk_mul_f32 v[144:145], v[138:139], v[164:165]
	v_pk_fma_f32 v[144:145], v[140:141], v[166:167], v[144:145]
	v_add_f32 v146, v144, v145
	ds_read_b128 v[208:211], v5 offset:21504
	ds_read_b128 v[212:215], v5 offset:21760
	ds_read_b128 v[216:219], v5 offset:22016
	ds_read_b128 v[220:223], v5 offset:22272
	ds_read_b128 v[224:227], v5 offset:22528
	ds_read_b32 v228, v9 offset:21504
	v_add_f32_dpp v146, v146, v146 quad_perm:[1,0,3,2] row_mask:0xf bank_mask:0xf bound_ctrl:1
	v_pk_mul_f32 v[246:247], v[138:139], v[246:247]
	v_pk_fma_f32 v[246:247], v[140:141], v[248:249], v[246:247]
	v_add_f32_dpp v146, v146, v146 quad_perm:[2,3,0,1] row_mask:0xf bank_mask:0xf bound_ctrl:1
	v_add_f32 v159, v246, v247
	v_pk_mul_f32 v[176:177], v[176:177], v[184:185] op_sel_hi:[1,0]
	v_add_f32_dpp v146, v146, v146 row_half_mirror row_mask:0xf bank_mask:0xf bound_ctrl:1
	v_pk_mul_f32 v[178:179], v[178:179], v[184:185] op_sel_hi:[1,0]
	s_waitcnt lgkmcnt(6)
	v_add_f32_dpp v146, v146, v146 row_mirror row_mask:0xf bank_mask:0xf bound_ctrl:1
	v_pk_fma_f32 v[176:177], v[146:147], v[168:169], v[176:177] op_sel_hi:[0,1,1] neg_lo:[1,0,0] neg_hi:[1,0,0]
	v_pk_fma_f32 v[178:179], v[146:147], v[170:171], v[178:179] op_sel_hi:[0,1,1] neg_lo:[1,0,0] neg_hi:[1,0,0]
	v_pk_fma_f32 v[138:139], v[138:139], v[172:173], v[176:177]
	v_pk_fma_f32 v[140:141], v[140:141], v[174:175], v[178:179]
	v_pk_mul_f32 v[144:145], v[138:139], v[186:187]
	v_pk_fma_f32 v[144:145], v[140:141], v[188:189], v[144:145]
	v_add_f32 v146, v144, v145
	ds_read_b128 v[230:233], v5 offset:23040
	ds_read_b128 v[234:237], v5 offset:23296
	ds_read_b128 v[238:241], v5 offset:23552
	ds_read_b128 v[242:245], v5 offset:23808
	ds_read_b128 v[246:249], v5 offset:24064
	ds_read_b32 v250, v9 offset:23040
	v_add_f32_dpp v146, v146, v146 quad_perm:[1,0,3,2] row_mask:0xf bank_mask:0xf bound_ctrl:1
	v_pk_mul_f32 v[180:181], v[138:139], v[180:181]
	v_pk_fma_f32 v[180:181], v[140:141], v[182:183], v[180:181]
	v_add_f32_dpp v146, v146, v146 quad_perm:[2,3,0,1] row_mask:0xf bank_mask:0xf bound_ctrl:1
	v_add_f32 v160, v180, v181
	v_pk_mul_f32 v[198:199], v[198:199], v[206:207] op_sel_hi:[1,0]
	v_add_f32_dpp v146, v146, v146 row_half_mirror row_mask:0xf bank_mask:0xf bound_ctrl:1
	v_pk_mul_f32 v[200:201], v[200:201], v[206:207] op_sel_hi:[1,0]
	s_waitcnt lgkmcnt(6)
	v_add_f32_dpp v146, v146, v146 row_mirror row_mask:0xf bank_mask:0xf bound_ctrl:1
	v_pk_fma_f32 v[198:199], v[146:147], v[190:191], v[198:199] op_sel_hi:[0,1,1] neg_lo:[1,0,0] neg_hi:[1,0,0]
	v_pk_fma_f32 v[200:201], v[146:147], v[192:193], v[200:201] op_sel_hi:[0,1,1] neg_lo:[1,0,0] neg_hi:[1,0,0]
	v_pk_fma_f32 v[138:139], v[138:139], v[194:195], v[198:199]
	v_pk_fma_f32 v[140:141], v[140:141], v[196:197], v[200:201]
	v_pk_mul_f32 v[144:145], v[138:139], v[208:209]
	v_pk_fma_f32 v[144:145], v[140:141], v[210:211], v[144:145]
	v_add_f32 v146, v144, v145
	ds_read_b128 v[164:167], v5 offset:24576
	ds_read_b128 v[168:171], v5 offset:24832
	ds_read_b128 v[172:175], v5 offset:25088
	ds_read_b128 v[176:179], v5 offset:25344
	ds_read_b128 v[180:183], v5 offset:25600
	ds_read_b32 v184, v9 offset:24576
	v_add_f32_dpp v146, v146, v146 quad_perm:[1,0,3,2] row_mask:0xf bank_mask:0xf bound_ctrl:1
	v_pk_mul_f32 v[202:203], v[138:139], v[202:203]
	v_pk_fma_f32 v[202:203], v[140:141], v[204:205], v[202:203]
	v_add_f32_dpp v146, v146, v146 quad_perm:[2,3,0,1] row_mask:0xf bank_mask:0xf bound_ctrl:1
	v_add_f32 v161, v202, v203
	v_pk_mul_f32 v[220:221], v[220:221], v[228:229] op_sel_hi:[1,0]
	v_add_f32_dpp v146, v146, v146 row_half_mirror row_mask:0xf bank_mask:0xf bound_ctrl:1
	v_pk_mul_f32 v[222:223], v[222:223], v[228:229] op_sel_hi:[1,0]
	s_waitcnt lgkmcnt(6)
	v_add_f32_dpp v146, v146, v146 row_mirror row_mask:0xf bank_mask:0xf bound_ctrl:1
	v_pk_fma_f32 v[220:221], v[146:147], v[212:213], v[220:221] op_sel_hi:[0,1,1] neg_lo:[1,0,0] neg_hi:[1,0,0]
	v_pk_fma_f32 v[222:223], v[146:147], v[214:215], v[222:223] op_sel_hi:[0,1,1] neg_lo:[1,0,0] neg_hi:[1,0,0]
	v_pk_fma_f32 v[138:139], v[138:139], v[216:217], v[220:221]
	v_pk_fma_f32 v[140:141], v[140:141], v[218:219], v[222:223]
	v_pk_mul_f32 v[144:145], v[138:139], v[230:231]
	v_pk_fma_f32 v[144:145], v[140:141], v[232:233], v[144:145]
	v_add_f32 v146, v144, v145
	ds_read_b128 v[186:189], v5 offset:26112
	ds_read_b128 v[190:193], v5 offset:26368
	ds_read_b128 v[194:197], v5 offset:26624
	ds_read_b128 v[198:201], v5 offset:26880
	ds_read_b128 v[202:205], v5 offset:27136
	ds_read_b32 v206, v9 offset:26112
	v_add_f32_dpp v146, v146, v146 quad_perm:[1,0,3,2] row_mask:0xf bank_mask:0xf bound_ctrl:1
	v_pk_mul_f32 v[224:225], v[138:139], v[224:225]
	v_pk_fma_f32 v[224:225], v[140:141], v[226:227], v[224:225]
	v_add_f32_dpp v146, v146, v146 quad_perm:[2,3,0,1] row_mask:0xf bank_mask:0xf bound_ctrl:1
	v_add_f32 v162, v224, v225
	v_pk_mul_f32 v[242:243], v[242:243], v[250:251] op_sel_hi:[1,0]
	v_add_f32_dpp v146, v146, v146 row_half_mirror row_mask:0xf bank_mask:0xf bound_ctrl:1
	v_pk_mul_f32 v[244:245], v[244:245], v[250:251] op_sel_hi:[1,0]
	s_waitcnt lgkmcnt(6)
	v_add_f32_dpp v146, v146, v146 row_mirror row_mask:0xf bank_mask:0xf bound_ctrl:1
	v_pk_fma_f32 v[242:243], v[146:147], v[234:235], v[242:243] op_sel_hi:[0,1,1] neg_lo:[1,0,0] neg_hi:[1,0,0]
	v_pk_fma_f32 v[244:245], v[146:147], v[236:237], v[244:245] op_sel_hi:[0,1,1] neg_lo:[1,0,0] neg_hi:[1,0,0]
	v_pk_fma_f32 v[138:139], v[138:139], v[238:239], v[242:243]
	v_pk_fma_f32 v[140:141], v[140:141], v[240:241], v[244:245]
	v_pk_mul_f32 v[144:145], v[138:139], v[164:165]
	v_pk_fma_f32 v[144:145], v[140:141], v[166:167], v[144:145]
	v_add_f32 v146, v144, v145
	ds_read_b128 v[208:211], v5 offset:27648
	ds_read_b128 v[212:215], v5 offset:27904
	ds_read_b128 v[216:219], v5 offset:28160
	ds_read_b128 v[220:223], v5 offset:28416
	ds_read_b128 v[224:227], v5 offset:28672
	ds_read_b32 v228, v9 offset:27648
	v_add_f32_dpp v146, v146, v146 quad_perm:[1,0,3,2] row_mask:0xf bank_mask:0xf bound_ctrl:1
	v_pk_mul_f32 v[246:247], v[138:139], v[246:247]
	v_pk_fma_f32 v[246:247], v[140:141], v[248:249], v[246:247]
	v_add_f32_dpp v146, v146, v146 quad_perm:[2,3,0,1] row_mask:0xf bank_mask:0xf bound_ctrl:1
	v_add_f32 v163, v246, v247
	v_pk_mul_f32 v[176:177], v[176:177], v[184:185] op_sel_hi:[1,0]
	v_add_f32_dpp v146, v146, v146 row_half_mirror row_mask:0xf bank_mask:0xf bound_ctrl:1
	v_pk_mul_f32 v[178:179], v[178:179], v[184:185] op_sel_hi:[1,0]
	s_waitcnt lgkmcnt(6)
	v_add_f32_dpp v146, v146, v146 row_mirror row_mask:0xf bank_mask:0xf bound_ctrl:1
	v_pk_fma_f32 v[176:177], v[146:147], v[168:169], v[176:177] op_sel_hi:[0,1,1] neg_lo:[1,0,0] neg_hi:[1,0,0]
	v_pk_fma_f32 v[178:179], v[146:147], v[170:171], v[178:179] op_sel_hi:[0,1,1] neg_lo:[1,0,0] neg_hi:[1,0,0]
	v_pk_fma_f32 v[138:139], v[138:139], v[172:173], v[176:177]
	v_pk_fma_f32 v[140:141], v[140:141], v[174:175], v[178:179]
	v_pk_mul_f32 v[144:145], v[138:139], v[186:187]
	v_pk_fma_f32 v[144:145], v[140:141], v[188:189], v[144:145]
	v_add_f32 v146, v144, v145
	v_add_f32_dpp v230, v148, v148 row_mirror row_mask:0xf bank_mask:0x3 bound_ctrl:1
	v_add_f32_dpp v230, v156, v156 row_mirror row_mask:0xf bank_mask:0xc bound_ctrl:1
	v_add_f32_dpp v231, v149, v149 row_mirror row_mask:0xf bank_mask:0x3 bound_ctrl:1
	v_add_f32_dpp v231, v157, v157 row_mirror row_mask:0xf bank_mask:0xc bound_ctrl:1
	v_add_f32_dpp v232, v150, v150 row_mirror row_mask:0xf bank_mask:0x3 bound_ctrl:1
	v_add_f32_dpp v232, v158, v158 row_mirror row_mask:0xf bank_mask:0xc bound_ctrl:1
	v_add_f32_dpp v233, v151, v151 row_mirror row_mask:0xf bank_mask:0x3 bound_ctrl:1
	v_add_f32_dpp v233, v159, v159 row_mirror row_mask:0xf bank_mask:0xc bound_ctrl:1
	v_add_f32_dpp v234, v152, v152 row_mirror row_mask:0xf bank_mask:0x3 bound_ctrl:1
	v_add_f32_dpp v234, v160, v160 row_mirror row_mask:0xf bank_mask:0xc bound_ctrl:1
	v_add_f32_dpp v235, v153, v153 row_mirror row_mask:0xf bank_mask:0x3 bound_ctrl:1
	v_add_f32_dpp v235, v161, v161 row_mirror row_mask:0xf bank_mask:0xc bound_ctrl:1
	v_add_f32_dpp v236, v154, v154 row_mirror row_mask:0xf bank_mask:0x3 bound_ctrl:1
	v_add_f32_dpp v236, v162, v162 row_mirror row_mask:0xf bank_mask:0xc bound_ctrl:1
	v_add_f32_dpp v237, v155, v155 row_mirror row_mask:0xf bank_mask:0x3 bound_ctrl:1
	v_add_f32_dpp v237, v163, v163 row_mirror row_mask:0xf bank_mask:0xc bound_ctrl:1
	v_add_f32_dpp v238, v230, v230 row_half_mirror row_mask:0xf bank_mask:0x5 bound_ctrl:1
	v_add_f32_dpp v238, v234, v234 row_half_mirror row_mask:0xf bank_mask:0xa bound_ctrl:1
	v_add_f32_dpp v239, v231, v231 row_half_mirror row_mask:0xf bank_mask:0x5 bound_ctrl:1
	v_add_f32_dpp v239, v235, v235 row_half_mirror row_mask:0xf bank_mask:0xa bound_ctrl:1
	v_add_f32_dpp v240, v232, v232 row_half_mirror row_mask:0xf bank_mask:0x5 bound_ctrl:1
	v_add_f32_dpp v240, v236, v236 row_half_mirror row_mask:0xf bank_mask:0xa bound_ctrl:1
	v_add_f32_dpp v241, v233, v233 row_half_mirror row_mask:0xf bank_mask:0x5 bound_ctrl:1
	v_add_f32_dpp v241, v237, v237 row_half_mirror row_mask:0xf bank_mask:0xa bound_ctrl:1
	s_mov_b32 vcc_lo, 0xcccccccc
	s_mov_b32 vcc_hi, 0xcccccccc
	v_cndmask_b32 v244, v240, v238, vcc
	v_cndmask_b32 v245, v241, v239, vcc
	v_cndmask_b32 v242, v238, v240, vcc
	v_cndmask_b32 v243, v239, v241, vcc
	v_add_f32_dpp v242, v244, v242 quad_perm:[2,3,0,1] row_mask:0xf bank_mask:0xf bound_ctrl:1
	v_add_f32_dpp v243, v245, v243 quad_perm:[2,3,0,1] row_mask:0xf bank_mask:0xf bound_ctrl:1
	s_mov_b32 vcc_lo, 0xaaaaaaaa
	s_mov_b32 vcc_hi, 0xaaaaaaaa
	v_cndmask_b32 v244, v243, v242, vcc
	v_cndmask_b32 v245, v242, v243, vcc
	s_nop 0
	v_add_f32_dpp v18, v244, v245 quad_perm:[1,0,3,2] row_mask:0xf bank_mask:0xf bound_ctrl:1
	ds_read_b128 v[230:233], v5 offset:29184
	ds_read_b128 v[234:237], v5 offset:29440
	ds_read_b128 v[238:241], v5 offset:29696
	ds_read_b128 v[242:245], v5 offset:29952
	ds_read_b128 v[246:249], v5 offset:30208
	ds_read_b32 v250, v9 offset:29184
	v_add_f32_dpp v146, v146, v146 quad_perm:[1,0,3,2] row_mask:0xf bank_mask:0xf bound_ctrl:1
	v_pk_mul_f32 v[180:181], v[138:139], v[180:181]
	v_pk_fma_f32 v[180:181], v[140:141], v[182:183], v[180:181]
	v_add_f32_dpp v146, v146, v146 quad_perm:[2,3,0,1] row_mask:0xf bank_mask:0xf bound_ctrl:1
	v_add_f32 v148, v180, v181
	v_pk_mul_f32 v[198:199], v[198:199], v[206:207] op_sel_hi:[1,0]
	v_add_f32_dpp v146, v146, v146 row_half_mirror row_mask:0xf bank_mask:0xf bound_ctrl:1
	v_pk_mul_f32 v[200:201], v[200:201], v[206:207] op_sel_hi:[1,0]
	s_waitcnt lgkmcnt(6)
	v_add_f32_dpp v146, v146, v146 row_mirror row_mask:0xf bank_mask:0xf bound_ctrl:1
	v_pk_fma_f32 v[198:199], v[146:147], v[190:191], v[198:199] op_sel_hi:[0,1,1] neg_lo:[1,0,0] neg_hi:[1,0,0]
	v_pk_fma_f32 v[200:201], v[146:147], v[192:193], v[200:201] op_sel_hi:[0,1,1] neg_lo:[1,0,0] neg_hi:[1,0,0]
	v_pk_fma_f32 v[138:139], v[138:139], v[194:195], v[198:199]
	v_pk_fma_f32 v[140:141], v[140:141], v[196:197], v[200:201]
	v_pk_mul_f32 v[144:145], v[138:139], v[208:209]
	v_pk_fma_f32 v[144:145], v[140:141], v[210:211], v[144:145]
	v_add_f32 v146, v144, v145
	ds_read_b128 v[164:167], v5 offset:30720
	ds_read_b128 v[168:171], v5 offset:30976
	ds_read_b128 v[172:175], v5 offset:31232
	ds_read_b128 v[176:179], v5 offset:31488
	ds_read_b128 v[180:183], v5 offset:31744
	ds_read_b32 v184, v9 offset:30720
	v_add_f32_dpp v146, v146, v146 quad_perm:[1,0,3,2] row_mask:0xf bank_mask:0xf bound_ctrl:1
	v_pk_mul_f32 v[202:203], v[138:139], v[202:203]
	v_pk_fma_f32 v[202:203], v[140:141], v[204:205], v[202:203]
	v_add_f32_dpp v146, v146, v146 quad_perm:[2,3,0,1] row_mask:0xf bank_mask:0xf bound_ctrl:1
	v_add_f32 v149, v202, v203
	v_pk_mul_f32 v[220:221], v[220:221], v[228:229] op_sel_hi:[1,0]
	v_add_f32_dpp v146, v146, v146 row_half_mirror row_mask:0xf bank_mask:0xf bound_ctrl:1
	v_pk_mul_f32 v[222:223], v[222:223], v[228:229] op_sel_hi:[1,0]
	s_waitcnt lgkmcnt(6)
	v_add_f32_dpp v146, v146, v146 row_mirror row_mask:0xf bank_mask:0xf bound_ctrl:1
	v_pk_fma_f32 v[220:221], v[146:147], v[212:213], v[220:221] op_sel_hi:[0,1,1] neg_lo:[1,0,0] neg_hi:[1,0,0]
	v_pk_fma_f32 v[222:223], v[146:147], v[214:215], v[222:223] op_sel_hi:[0,1,1] neg_lo:[1,0,0] neg_hi:[1,0,0]
	v_pk_fma_f32 v[138:139], v[138:139], v[216:217], v[220:221]
	v_pk_fma_f32 v[140:141], v[140:141], v[218:219], v[222:223]
	v_pk_mul_f32 v[144:145], v[138:139], v[230:231]
	v_pk_fma_f32 v[144:145], v[140:141], v[232:233], v[144:145]
	v_add_f32 v146, v144, v145
	ds_read_b128 v[186:189], v5 offset:32256
	ds_read_b128 v[190:193], v5 offset:32512
	ds_read_b128 v[194:197], v5 offset:32768
	ds_read_b128 v[198:201], v5 offset:33024
	ds_read_b128 v[202:205], v5 offset:33280
	ds_read_b32 v206, v9 offset:32256
	v_add_f32_dpp v146, v146, v146 quad_perm:[1,0,3,2] row_mask:0xf bank_mask:0xf bound_ctrl:1
	v_pk_mul_f32 v[224:225], v[138:139], v[224:225]
	v_pk_fma_f32 v[224:225], v[140:141], v[226:227], v[224:225]
	v_add_f32_dpp v146, v146, v146 quad_perm:[2,3,0,1] row_mask:0xf bank_mask:0xf bound_ctrl:1
	v_add_f32 v150, v224, v225
	v_pk_mul_f32 v[242:243], v[242:243], v[250:251] op_sel_hi:[1,0]
	v_add_f32_dpp v146, v146, v146 row_half_mirror row_mask:0xf bank_mask:0xf bound_ctrl:1
	v_pk_mul_f32 v[244:245], v[244:245], v[250:251] op_sel_hi:[1,0]
	s_waitcnt lgkmcnt(6)
	v_add_f32_dpp v146, v146, v146 row_mirror row_mask:0xf bank_mask:0xf bound_ctrl:1
	v_pk_fma_f32 v[242:243], v[146:147], v[234:235], v[242:243] op_sel_hi:[0,1,1] neg_lo:[1,0,0] neg_hi:[1,0,0]
	v_pk_fma_f32 v[244:245], v[146:147], v[236:237], v[244:245] op_sel_hi:[0,1,1] neg_lo:[1,0,0] neg_hi:[1,0,0]
	v_pk_fma_f32 v[138:139], v[138:139], v[238:239], v[242:243]
	v_pk_fma_f32 v[140:141], v[140:141], v[240:241], v[244:245]
	v_pk_mul_f32 v[144:145], v[138:139], v[164:165]
	v_pk_fma_f32 v[144:145], v[140:141], v[166:167], v[144:145]
	v_add_f32 v146, v144, v145
	ds_read_b128 v[208:211], v5 offset:33792
	ds_read_b128 v[212:215], v5 offset:34048
	ds_read_b128 v[216:219], v5 offset:34304
	ds_read_b128 v[220:223], v5 offset:34560
	ds_read_b128 v[224:227], v5 offset:34816
	ds_read_b32 v228, v9 offset:33792
	v_add_f32_dpp v146, v146, v146 quad_perm:[1,0,3,2] row_mask:0xf bank_mask:0xf bound_ctrl:1
	v_pk_mul_f32 v[246:247], v[138:139], v[246:247]
	v_pk_fma_f32 v[246:247], v[140:141], v[248:249], v[246:247]
	v_add_f32_dpp v146, v146, v146 quad_perm:[2,3,0,1] row_mask:0xf bank_mask:0xf bound_ctrl:1
	v_add_f32 v151, v246, v247
	v_pk_mul_f32 v[176:177], v[176:177], v[184:185] op_sel_hi:[1,0]
	v_add_f32_dpp v146, v146, v146 row_half_mirror row_mask:0xf bank_mask:0xf bound_ctrl:1
	v_pk_mul_f32 v[178:179], v[178:179], v[184:185] op_sel_hi:[1,0]
	s_waitcnt lgkmcnt(6)
	v_add_f32_dpp v146, v146, v146 row_mirror row_mask:0xf bank_mask:0xf bound_ctrl:1
	v_pk_fma_f32 v[176:177], v[146:147], v[168:169], v[176:177] op_sel_hi:[0,1,1] neg_lo:[1,0,0] neg_hi:[1,0,0]
	v_pk_fma_f32 v[178:179], v[146:147], v[170:171], v[178:179] op_sel_hi:[0,1,1] neg_lo:[1,0,0] neg_hi:[1,0,0]
	v_pk_fma_f32 v[138:139], v[138:139], v[172:173], v[176:177]
	v_pk_fma_f32 v[140:141], v[140:141], v[174:175], v[178:179]
	v_pk_mul_f32 v[144:145], v[138:139], v[186:187]
	v_pk_fma_f32 v[144:145], v[140:141], v[188:189], v[144:145]
	v_add_f32 v146, v144, v145
	ds_read_b128 v[230:233], v5 offset:35328
	ds_read_b128 v[234:237], v5 offset:35584
	ds_read_b128 v[238:241], v5 offset:35840
	ds_read_b128 v[242:245], v5 offset:36096
	ds_read_b128 v[246:249], v5 offset:36352
	ds_read_b32 v250, v9 offset:35328
	v_add_f32_dpp v146, v146, v146 quad_perm:[1,0,3,2] row_mask:0xf bank_mask:0xf bound_ctrl:1
	v_pk_mul_f32 v[180:181], v[138:139], v[180:181]
	v_pk_fma_f32 v[180:181], v[140:141], v[182:183], v[180:181]
	v_add_f32_dpp v146, v146, v146 quad_perm:[2,3,0,1] row_mask:0xf bank_mask:0xf bound_ctrl:1
	v_add_f32 v152, v180, v181
	v_pk_mul_f32 v[198:199], v[198:199], v[206:207] op_sel_hi:[1,0]
	v_add_f32_dpp v146, v146, v146 row_half_mirror row_mask:0xf bank_mask:0xf bound_ctrl:1
	v_pk_mul_f32 v[200:201], v[200:201], v[206:207] op_sel_hi:[1,0]
	s_waitcnt lgkmcnt(6)
	v_add_f32_dpp v146, v146, v146 row_mirror row_mask:0xf bank_mask:0xf bound_ctrl:1
	v_pk_fma_f32 v[198:199], v[146:147], v[190:191], v[198:199] op_sel_hi:[0,1,1] neg_lo:[1,0,0] neg_hi:[1,0,0]
	v_pk_fma_f32 v[200:201], v[146:147], v[192:193], v[200:201] op_sel_hi:[0,1,1] neg_lo:[1,0,0] neg_hi:[1,0,0]
	v_pk_fma_f32 v[138:139], v[138:139], v[194:195], v[198:199]
	v_pk_fma_f32 v[140:141], v[140:141], v[196:197], v[200:201]
	v_pk_mul_f32 v[144:145], v[138:139], v[208:209]
	v_pk_fma_f32 v[144:145], v[140:141], v[210:211], v[144:145]
	v_add_f32 v146, v144, v145
	ds_read_b128 v[164:167], v5 offset:36864
	ds_read_b128 v[168:171], v5 offset:37120
	ds_read_b128 v[172:175], v5 offset:37376
	ds_read_b128 v[176:179], v5 offset:37632
	ds_read_b128 v[180:183], v5 offset:37888
	ds_read_b32 v184, v9 offset:36864
	v_add_f32_dpp v146, v146, v146 quad_perm:[1,0,3,2] row_mask:0xf bank_mask:0xf bound_ctrl:1
	v_pk_mul_f32 v[202:203], v[138:139], v[202:203]
	v_pk_fma_f32 v[202:203], v[140:141], v[204:205], v[202:203]
	v_add_f32_dpp v146, v146, v146 quad_perm:[2,3,0,1] row_mask:0xf bank_mask:0xf bound_ctrl:1
	v_add_f32 v153, v202, v203
	v_pk_mul_f32 v[220:221], v[220:221], v[228:229] op_sel_hi:[1,0]
	v_add_f32_dpp v146, v146, v146 row_half_mirror row_mask:0xf bank_mask:0xf bound_ctrl:1
	v_pk_mul_f32 v[222:223], v[222:223], v[228:229] op_sel_hi:[1,0]
	s_waitcnt lgkmcnt(6)
	v_add_f32_dpp v146, v146, v146 row_mirror row_mask:0xf bank_mask:0xf bound_ctrl:1
	v_pk_fma_f32 v[220:221], v[146:147], v[212:213], v[220:221] op_sel_hi:[0,1,1] neg_lo:[1,0,0] neg_hi:[1,0,0]
	v_pk_fma_f32 v[222:223], v[146:147], v[214:215], v[222:223] op_sel_hi:[0,1,1] neg_lo:[1,0,0] neg_hi:[1,0,0]
	v_pk_fma_f32 v[138:139], v[138:139], v[216:217], v[220:221]
	v_pk_fma_f32 v[140:141], v[140:141], v[218:219], v[222:223]
	v_pk_mul_f32 v[144:145], v[138:139], v[230:231]
	v_pk_fma_f32 v[144:145], v[140:141], v[232:233], v[144:145]
	v_add_f32 v146, v144, v145
	ds_read_b128 v[186:189], v5 offset:38400
	ds_read_b128 v[190:193], v5 offset:38656
	ds_read_b128 v[194:197], v5 offset:38912
	ds_read_b128 v[198:201], v5 offset:39168
	ds_read_b128 v[202:205], v5 offset:39424
	ds_read_b32 v206, v9 offset:38400
	v_add_f32_dpp v146, v146, v146 quad_perm:[1,0,3,2] row_mask:0xf bank_mask:0xf bound_ctrl:1
	v_pk_mul_f32 v[224:225], v[138:139], v[224:225]
	v_pk_fma_f32 v[224:225], v[140:141], v[226:227], v[224:225]
	v_add_f32_dpp v146, v146, v146 quad_perm:[2,3,0,1] row_mask:0xf bank_mask:0xf bound_ctrl:1
	v_add_f32 v154, v224, v225
	v_pk_mul_f32 v[242:243], v[242:243], v[250:251] op_sel_hi:[1,0]
	v_add_f32_dpp v146, v146, v146 row_half_mirror row_mask:0xf bank_mask:0xf bound_ctrl:1
	v_pk_mul_f32 v[244:245], v[244:245], v[250:251] op_sel_hi:[1,0]
	s_waitcnt lgkmcnt(6)
	v_add_f32_dpp v146, v146, v146 row_mirror row_mask:0xf bank_mask:0xf bound_ctrl:1
	v_pk_fma_f32 v[242:243], v[146:147], v[234:235], v[242:243] op_sel_hi:[0,1,1] neg_lo:[1,0,0] neg_hi:[1,0,0]
	v_pk_fma_f32 v[244:245], v[146:147], v[236:237], v[244:245] op_sel_hi:[0,1,1] neg_lo:[1,0,0] neg_hi:[1,0,0]
	v_pk_fma_f32 v[138:139], v[138:139], v[238:239], v[242:243]
	v_pk_fma_f32 v[140:141], v[140:141], v[240:241], v[244:245]
	v_pk_mul_f32 v[144:145], v[138:139], v[164:165]
	v_pk_fma_f32 v[144:145], v[140:141], v[166:167], v[144:145]
	v_add_f32 v146, v144, v145
	ds_read_b128 v[208:211], v5 offset:39936
	ds_read_b128 v[212:215], v5 offset:40192
	ds_read_b128 v[216:219], v5 offset:40448
	ds_read_b128 v[220:223], v5 offset:40704
	ds_read_b128 v[224:227], v5 offset:40960
	ds_read_b32 v228, v9 offset:39936
	v_add_f32_dpp v146, v146, v146 quad_perm:[1,0,3,2] row_mask:0xf bank_mask:0xf bound_ctrl:1
	v_pk_mul_f32 v[246:247], v[138:139], v[246:247]
	v_pk_fma_f32 v[246:247], v[140:141], v[248:249], v[246:247]
	v_add_f32_dpp v146, v146, v146 quad_perm:[2,3,0,1] row_mask:0xf bank_mask:0xf bound_ctrl:1
	v_add_f32 v155, v246, v247
	v_pk_mul_f32 v[176:177], v[176:177], v[184:185] op_sel_hi:[1,0]
	v_add_f32_dpp v146, v146, v146 row_half_mirror row_mask:0xf bank_mask:0xf bound_ctrl:1
	v_pk_mul_f32 v[178:179], v[178:179], v[184:185] op_sel_hi:[1,0]
	s_waitcnt lgkmcnt(6)
	v_add_f32_dpp v146, v146, v146 row_mirror row_mask:0xf bank_mask:0xf bound_ctrl:1
	v_pk_fma_f32 v[176:177], v[146:147], v[168:169], v[176:177] op_sel_hi:[0,1,1] neg_lo:[1,0,0] neg_hi:[1,0,0]
	v_pk_fma_f32 v[178:179], v[146:147], v[170:171], v[178:179] op_sel_hi:[0,1,1] neg_lo:[1,0,0] neg_hi:[1,0,0]
	v_pk_fma_f32 v[138:139], v[138:139], v[172:173], v[176:177]
	v_pk_fma_f32 v[140:141], v[140:141], v[174:175], v[178:179]
	v_pk_mul_f32 v[144:145], v[138:139], v[186:187]
	v_pk_fma_f32 v[144:145], v[140:141], v[188:189], v[144:145]
	v_add_f32 v146, v144, v145
	ds_read_b128 v[230:233], v5 offset:41472
	ds_read_b128 v[234:237], v5 offset:41728
	ds_read_b128 v[238:241], v5 offset:41984
	ds_read_b128 v[242:245], v5 offset:42240
	ds_read_b128 v[246:249], v5 offset:42496
	ds_read_b32 v250, v9 offset:41472
	v_add_f32_dpp v146, v146, v146 quad_perm:[1,0,3,2] row_mask:0xf bank_mask:0xf bound_ctrl:1
	v_pk_mul_f32 v[180:181], v[138:139], v[180:181]
	v_pk_fma_f32 v[180:181], v[140:141], v[182:183], v[180:181]
	v_add_f32_dpp v146, v146, v146 quad_perm:[2,3,0,1] row_mask:0xf bank_mask:0xf bound_ctrl:1
	v_add_f32 v156, v180, v181
	v_pk_mul_f32 v[198:199], v[198:199], v[206:207] op_sel_hi:[1,0]
	v_add_f32_dpp v146, v146, v146 row_half_mirror row_mask:0xf bank_mask:0xf bound_ctrl:1
	v_pk_mul_f32 v[200:201], v[200:201], v[206:207] op_sel_hi:[1,0]
	s_waitcnt lgkmcnt(6)
	v_add_f32_dpp v146, v146, v146 row_mirror row_mask:0xf bank_mask:0xf bound_ctrl:1
	v_pk_fma_f32 v[198:199], v[146:147], v[190:191], v[198:199] op_sel_hi:[0,1,1] neg_lo:[1,0,0] neg_hi:[1,0,0]
	v_pk_fma_f32 v[200:201], v[146:147], v[192:193], v[200:201] op_sel_hi:[0,1,1] neg_lo:[1,0,0] neg_hi:[1,0,0]
	v_pk_fma_f32 v[138:139], v[138:139], v[194:195], v[198:199]
	v_pk_fma_f32 v[140:141], v[140:141], v[196:197], v[200:201]
	v_pk_mul_f32 v[144:145], v[138:139], v[208:209]
	v_pk_fma_f32 v[144:145], v[140:141], v[210:211], v[144:145]
	v_add_f32 v146, v144, v145
	ds_read_b128 v[164:167], v5 offset:43008
	ds_read_b128 v[168:171], v5 offset:43264
	ds_read_b128 v[172:175], v5 offset:43520
	ds_read_b128 v[176:179], v5 offset:43776
	ds_read_b128 v[180:183], v5 offset:44032
	ds_read_b32 v184, v9 offset:43008
	v_add_f32_dpp v146, v146, v146 quad_perm:[1,0,3,2] row_mask:0xf bank_mask:0xf bound_ctrl:1
	v_pk_mul_f32 v[202:203], v[138:139], v[202:203]
	v_pk_fma_f32 v[202:203], v[140:141], v[204:205], v[202:203]
	v_add_f32_dpp v146, v146, v146 quad_perm:[2,3,0,1] row_mask:0xf bank_mask:0xf bound_ctrl:1
	v_add_f32 v157, v202, v203
	v_pk_mul_f32 v[220:221], v[220:221], v[228:229] op_sel_hi:[1,0]
	v_add_f32_dpp v146, v146, v146 row_half_mirror row_mask:0xf bank_mask:0xf bound_ctrl:1
	v_pk_mul_f32 v[222:223], v[222:223], v[228:229] op_sel_hi:[1,0]
	s_waitcnt lgkmcnt(6)
	v_add_f32_dpp v146, v146, v146 row_mirror row_mask:0xf bank_mask:0xf bound_ctrl:1
	v_pk_fma_f32 v[220:221], v[146:147], v[212:213], v[220:221] op_sel_hi:[0,1,1] neg_lo:[1,0,0] neg_hi:[1,0,0]
	v_pk_fma_f32 v[222:223], v[146:147], v[214:215], v[222:223] op_sel_hi:[0,1,1] neg_lo:[1,0,0] neg_hi:[1,0,0]
	v_pk_fma_f32 v[138:139], v[138:139], v[216:217], v[220:221]
	v_pk_fma_f32 v[140:141], v[140:141], v[218:219], v[222:223]
	v_pk_mul_f32 v[144:145], v[138:139], v[230:231]
	v_pk_fma_f32 v[144:145], v[140:141], v[232:233], v[144:145]
	v_add_f32 v146, v144, v145
	ds_read_b128 v[186:189], v5 offset:44544
	ds_read_b128 v[190:193], v5 offset:44800
	ds_read_b128 v[194:197], v5 offset:45056
	ds_read_b128 v[198:201], v5 offset:45312
	ds_read_b128 v[202:205], v5 offset:45568
	ds_read_b32 v206, v9 offset:44544
	v_add_f32_dpp v146, v146, v146 quad_perm:[1,0,3,2] row_mask:0xf bank_mask:0xf bound_ctrl:1
	v_pk_mul_f32 v[224:225], v[138:139], v[224:225]
	v_pk_fma_f32 v[224:225], v[140:141], v[226:227], v[224:225]
	v_add_f32_dpp v146, v146, v146 quad_perm:[2,3,0,1] row_mask:0xf bank_mask:0xf bound_ctrl:1
	v_add_f32 v158, v224, v225
	v_pk_mul_f32 v[242:243], v[242:243], v[250:251] op_sel_hi:[1,0]
	v_add_f32_dpp v146, v146, v146 row_half_mirror row_mask:0xf bank_mask:0xf bound_ctrl:1
	v_pk_mul_f32 v[244:245], v[244:245], v[250:251] op_sel_hi:[1,0]
	s_waitcnt lgkmcnt(6)
	v_add_f32_dpp v146, v146, v146 row_mirror row_mask:0xf bank_mask:0xf bound_ctrl:1
	v_pk_fma_f32 v[242:243], v[146:147], v[234:235], v[242:243] op_sel_hi:[0,1,1] neg_lo:[1,0,0] neg_hi:[1,0,0]
	v_pk_fma_f32 v[244:245], v[146:147], v[236:237], v[244:245] op_sel_hi:[0,1,1] neg_lo:[1,0,0] neg_hi:[1,0,0]
	v_pk_fma_f32 v[138:139], v[138:139], v[238:239], v[242:243]
	v_pk_fma_f32 v[140:141], v[140:141], v[240:241], v[244:245]
	v_pk_mul_f32 v[144:145], v[138:139], v[164:165]
	v_pk_fma_f32 v[144:145], v[140:141], v[166:167], v[144:145]
	v_add_f32 v146, v144, v145
	ds_read_b128 v[208:211], v5 offset:46080
	ds_read_b128 v[212:215], v5 offset:46336
	ds_read_b128 v[216:219], v5 offset:46592
	ds_read_b128 v[220:223], v5 offset:46848
	ds_read_b128 v[224:227], v5 offset:47104
	ds_read_b32 v228, v9 offset:46080
	v_add_f32_dpp v146, v146, v146 quad_perm:[1,0,3,2] row_mask:0xf bank_mask:0xf bound_ctrl:1
	v_pk_mul_f32 v[246:247], v[138:139], v[246:247]
	v_pk_fma_f32 v[246:247], v[140:141], v[248:249], v[246:247]
	v_add_f32_dpp v146, v146, v146 quad_perm:[2,3,0,1] row_mask:0xf bank_mask:0xf bound_ctrl:1
	v_add_f32 v159, v246, v247
	v_pk_mul_f32 v[176:177], v[176:177], v[184:185] op_sel_hi:[1,0]
	v_add_f32_dpp v146, v146, v146 row_half_mirror row_mask:0xf bank_mask:0xf bound_ctrl:1
	v_pk_mul_f32 v[178:179], v[178:179], v[184:185] op_sel_hi:[1,0]
	s_waitcnt lgkmcnt(6)
	v_add_f32_dpp v146, v146, v146 row_mirror row_mask:0xf bank_mask:0xf bound_ctrl:1
	v_pk_fma_f32 v[176:177], v[146:147], v[168:169], v[176:177] op_sel_hi:[0,1,1] neg_lo:[1,0,0] neg_hi:[1,0,0]
	v_pk_fma_f32 v[178:179], v[146:147], v[170:171], v[178:179] op_sel_hi:[0,1,1] neg_lo:[1,0,0] neg_hi:[1,0,0]
	v_pk_fma_f32 v[138:139], v[138:139], v[172:173], v[176:177]
	v_pk_fma_f32 v[140:141], v[140:141], v[174:175], v[178:179]
	v_pk_mul_f32 v[144:145], v[138:139], v[186:187]
	v_pk_fma_f32 v[144:145], v[140:141], v[188:189], v[144:145]
	v_add_f32 v146, v144, v145
	ds_read_b128 v[230:233], v5 offset:47616
	ds_read_b128 v[234:237], v5 offset:47872
	ds_read_b128 v[238:241], v5 offset:48128
	ds_read_b128 v[242:245], v5 offset:48384
	ds_read_b128 v[246:249], v5 offset:48640
	ds_read_b32 v250, v9 offset:47616
	v_add_f32_dpp v146, v146, v146 quad_perm:[1,0,3,2] row_mask:0xf bank_mask:0xf bound_ctrl:1
	v_pk_mul_f32 v[180:181], v[138:139], v[180:181]
	v_pk_fma_f32 v[180:181], v[140:141], v[182:183], v[180:181]
	v_add_f32_dpp v146, v146, v146 quad_perm:[2,3,0,1] row_mask:0xf bank_mask:0xf bound_ctrl:1
	v_add_f32 v160, v180, v181
	v_pk_mul_f32 v[198:199], v[198:199], v[206:207] op_sel_hi:[1,0]
	v_add_f32_dpp v146, v146, v146 row_half_mirror row_mask:0xf bank_mask:0xf bound_ctrl:1
	v_pk_mul_f32 v[200:201], v[200:201], v[206:207] op_sel_hi:[1,0]
	s_waitcnt lgkmcnt(6)
	v_add_f32_dpp v146, v146, v146 row_mirror row_mask:0xf bank_mask:0xf bound_ctrl:1
	v_pk_fma_f32 v[198:199], v[146:147], v[190:191], v[198:199] op_sel_hi:[0,1,1] neg_lo:[1,0,0] neg_hi:[1,0,0]
	v_pk_fma_f32 v[200:201], v[146:147], v[192:193], v[200:201] op_sel_hi:[0,1,1] neg_lo:[1,0,0] neg_hi:[1,0,0]
	v_pk_fma_f32 v[138:139], v[138:139], v[194:195], v[198:199]
	v_pk_fma_f32 v[140:141], v[140:141], v[196:197], v[200:201]
	v_pk_mul_f32 v[144:145], v[138:139], v[208:209]
	v_pk_fma_f32 v[144:145], v[140:141], v[210:211], v[144:145]
	v_add_f32 v146, v144, v145
	s_nop 1
	v_add_f32_dpp v146, v146, v146 quad_perm:[1,0,3,2] row_mask:0xf bank_mask:0xf bound_ctrl:1
	v_pk_mul_f32 v[202:203], v[138:139], v[202:203]
	v_pk_fma_f32 v[202:203], v[140:141], v[204:205], v[202:203]
	v_add_f32_dpp v146, v146, v146 quad_perm:[2,3,0,1] row_mask:0xf bank_mask:0xf bound_ctrl:1
	v_add_f32 v161, v202, v203
	v_pk_mul_f32 v[220:221], v[220:221], v[228:229] op_sel_hi:[1,0]
	v_add_f32_dpp v146, v146, v146 row_half_mirror row_mask:0xf bank_mask:0xf bound_ctrl:1
	v_pk_mul_f32 v[222:223], v[222:223], v[228:229] op_sel_hi:[1,0]
	s_waitcnt lgkmcnt(0)
	v_add_f32_dpp v146, v146, v146 row_mirror row_mask:0xf bank_mask:0xf bound_ctrl:1
	v_pk_fma_f32 v[220:221], v[146:147], v[212:213], v[220:221] op_sel_hi:[0,1,1] neg_lo:[1,0,0] neg_hi:[1,0,0]
	v_pk_fma_f32 v[222:223], v[146:147], v[214:215], v[222:223] op_sel_hi:[0,1,1] neg_lo:[1,0,0] neg_hi:[1,0,0]
	v_pk_fma_f32 v[138:139], v[138:139], v[216:217], v[220:221]
	v_pk_fma_f32 v[140:141], v[140:141], v[218:219], v[222:223]
	v_pk_mul_f32 v[144:145], v[138:139], v[230:231]
	v_pk_fma_f32 v[144:145], v[140:141], v[232:233], v[144:145]
	v_add_f32 v146, v144, v145
	s_nop 1
	v_add_f32_dpp v146, v146, v146 quad_perm:[1,0,3,2] row_mask:0xf bank_mask:0xf bound_ctrl:1
	v_pk_mul_f32 v[224:225], v[138:139], v[224:225]
	v_pk_fma_f32 v[224:225], v[140:141], v[226:227], v[224:225]
	v_add_f32_dpp v146, v146, v146 quad_perm:[2,3,0,1] row_mask:0xf bank_mask:0xf bound_ctrl:1
	v_add_f32 v162, v224, v225
	v_pk_mul_f32 v[242:243], v[242:243], v[250:251] op_sel_hi:[1,0]
	v_add_f32_dpp v146, v146, v146 row_half_mirror row_mask:0xf bank_mask:0xf bound_ctrl:1
	v_pk_mul_f32 v[244:245], v[244:245], v[250:251] op_sel_hi:[1,0]
	s_nop 0
	v_add_f32_dpp v146, v146, v146 row_mirror row_mask:0xf bank_mask:0xf bound_ctrl:1
	v_pk_fma_f32 v[242:243], v[146:147], v[234:235], v[242:243] op_sel_hi:[0,1,1] neg_lo:[1,0,0] neg_hi:[1,0,0]
	v_pk_fma_f32 v[244:245], v[146:147], v[236:237], v[244:245] op_sel_hi:[0,1,1] neg_lo:[1,0,0] neg_hi:[1,0,0]
	v_pk_fma_f32 v[138:139], v[138:139], v[238:239], v[242:243]
	v_pk_fma_f32 v[140:141], v[140:141], v[240:241], v[244:245]
	v_pk_mul_f32 v[246:247], v[138:139], v[246:247]
	v_pk_fma_f32 v[246:247], v[140:141], v[248:249], v[246:247]
	v_add_f32 v163, v246, v247
	s_nop 0
	v_add_f32_dpp v230, v148, v148 row_mirror row_mask:0xf bank_mask:0x3 bound_ctrl:1
	v_add_f32_dpp v230, v156, v156 row_mirror row_mask:0xf bank_mask:0xc bound_ctrl:1
	v_add_f32_dpp v231, v149, v149 row_mirror row_mask:0xf bank_mask:0x3 bound_ctrl:1
	v_add_f32_dpp v231, v157, v157 row_mirror row_mask:0xf bank_mask:0xc bound_ctrl:1
	v_add_f32_dpp v232, v150, v150 row_mirror row_mask:0xf bank_mask:0x3 bound_ctrl:1
	v_add_f32_dpp v232, v158, v158 row_mirror row_mask:0xf bank_mask:0xc bound_ctrl:1
	v_add_f32_dpp v233, v151, v151 row_mirror row_mask:0xf bank_mask:0x3 bound_ctrl:1
	v_add_f32_dpp v233, v159, v159 row_mirror row_mask:0xf bank_mask:0xc bound_ctrl:1
	v_add_f32_dpp v234, v152, v152 row_mirror row_mask:0xf bank_mask:0x3 bound_ctrl:1
	v_add_f32_dpp v234, v160, v160 row_mirror row_mask:0xf bank_mask:0xc bound_ctrl:1
	v_add_f32_dpp v235, v153, v153 row_mirror row_mask:0xf bank_mask:0x3 bound_ctrl:1
	v_add_f32_dpp v235, v161, v161 row_mirror row_mask:0xf bank_mask:0xc bound_ctrl:1
	v_add_f32_dpp v236, v154, v154 row_mirror row_mask:0xf bank_mask:0x3 bound_ctrl:1
	v_add_f32_dpp v236, v162, v162 row_mirror row_mask:0xf bank_mask:0xc bound_ctrl:1
	v_add_f32_dpp v237, v155, v155 row_mirror row_mask:0xf bank_mask:0x3 bound_ctrl:1
	v_add_f32_dpp v237, v163, v163 row_mirror row_mask:0xf bank_mask:0xc bound_ctrl:1
	v_add_f32_dpp v238, v230, v230 row_half_mirror row_mask:0xf bank_mask:0x5 bound_ctrl:1
	v_add_f32_dpp v238, v234, v234 row_half_mirror row_mask:0xf bank_mask:0xa bound_ctrl:1
	v_add_f32_dpp v239, v231, v231 row_half_mirror row_mask:0xf bank_mask:0x5 bound_ctrl:1
	v_add_f32_dpp v239, v235, v235 row_half_mirror row_mask:0xf bank_mask:0xa bound_ctrl:1
	v_add_f32_dpp v240, v232, v232 row_half_mirror row_mask:0xf bank_mask:0x5 bound_ctrl:1
	v_add_f32_dpp v240, v236, v236 row_half_mirror row_mask:0xf bank_mask:0xa bound_ctrl:1
	v_add_f32_dpp v241, v233, v233 row_half_mirror row_mask:0xf bank_mask:0x5 bound_ctrl:1
	v_add_f32_dpp v241, v237, v237 row_half_mirror row_mask:0xf bank_mask:0xa bound_ctrl:1
	s_mov_b32 vcc_lo, 0xcccccccc
	s_mov_b32 vcc_hi, 0xcccccccc
	v_cndmask_b32 v244, v240, v238, vcc
	v_cndmask_b32 v245, v241, v239, vcc
	v_cndmask_b32 v242, v238, v240, vcc
	v_cndmask_b32 v243, v239, v241, vcc
	v_add_f32_dpp v242, v244, v242 quad_perm:[2,3,0,1] row_mask:0xf bank_mask:0xf bound_ctrl:1
	v_add_f32_dpp v243, v245, v243 quad_perm:[2,3,0,1] row_mask:0xf bank_mask:0xf bound_ctrl:1
	s_mov_b32 vcc_lo, 0xaaaaaaaa
	s_mov_b32 vcc_hi, 0xaaaaaaaa
	v_cndmask_b32 v244, v243, v242, vcc
	v_cndmask_b32 v245, v242, v243, vcc
	s_nop 0
	v_add_f32_dpp v19, v244, v245 quad_perm:[1,0,3,2] row_mask:0xf bank_mask:0xf bound_ctrl:1

; #define SCAN_BAR() asm volatile("s_barrier" ::: "memory")
; __device__ __forceinline__ void scan_unit(const Ctx& C0, const float* scn, int T, int quarter, const float* S0, float* Sout, unsigned char* obase, int mode) {
;     ...
;             const unsigned aq = (unsigned)(size_t)(C.lds + (k & 1) * SLOT_B) + 16u * (unsigned)q, av = (unsigned)(size_t)(C.lds + (k & 1) * SLOT_B) + (320u + (unsigned)irow) * 4u;
;             float osel0, osel1;
;             asm volatile(SCAN_CHUNK_ASM : "+v"(S0x), "+v"(S1x), "+v"(S2x), "+v"(S3x), "=&v"(osel0), "=&v"(osel1) : "v"(aq), "v"(av), "v"(q) : SCAN_CHUNK_CLOBBERS, "memory");
;             if (mode == 0) { *(float*)(obase + (size_t)(k * 32 + q) * UPITCH_B + rl * 4) = osel0; *(float*)(obase + (size_t)(k * 32 + 16 + q) * UPITCH_B + rl * 4) = osel1; }
;             SCAN_BAR();
	v_lshl_add_u64 v[14:15], v[6:7], 0, s[0:1]
	v_add_co_u32_e32 v16, vcc, 0xfc29000, v14
	s_mov_b32 s8, 0xfc7f000
	s_nop 0
	v_addc_co_u32_e32 v17, vcc, 0, v15, vcc
	global_store_dword v[16:17], v18, off offset:768
	v_add_co_u32_e32 v16, vcc, 0xfc54000, v14
	s_add_u32 s0, s0, 0xac000
	s_nop 0
	v_addc_co_u32_e32 v17, vcc, 0, v15, vcc
	global_store_dword v[16:17], v19, off offset:768
	s_barrier
	ds_read_b128 v[164:167], v10 offset:0
	ds_read_b128 v[168:171], v10 offset:256
	ds_read_b128 v[172:175], v10 offset:512
	ds_read_b128 v[176:179], v10 offset:768
	ds_read_b128 v[180:183], v10 offset:1024
	ds_read_b32 v184, v11 offset:0
	ds_read_b128 v[186:189], v10 offset:1536
	ds_read_b128 v[190:193], v10 offset:1792
	ds_read_b128 v[194:197], v10 offset:2048
	ds_read_b128 v[198:201], v10 offset:2304
	ds_read_b128 v[202:205], v10 offset:2560
	ds_read_b32 v206, v11 offset:1536
	s_waitcnt lgkmcnt(6)
	v_pk_mul_f32 v[144:145], v[138:139], v[164:165]
	v_pk_fma_f32 v[144:145], v[140:141], v[166:167], v[144:145]
	v_add_f32 v146, v144, v145
	ds_read_b128 v[208:211], v10 offset:3072
	ds_read_b128 v[212:215], v10 offset:3328
	ds_read_b128 v[216:219], v10 offset:3584
	ds_read_b128 v[220:223], v10 offset:3840
	ds_read_b128 v[224:227], v10 offset:4096
	ds_read_b32 v228, v11 offset:3072
	v_add_f32_dpp v146, v146, v146 quad_perm:[1,0,3,2] row_mask:0xf bank_mask:0xf bound_ctrl:1
	s_nop 0
	s_nop 0
	v_add_f32_dpp v146, v146, v146 quad_perm:[2,3,0,1] row_mask:0xf bank_mask:0xf bound_ctrl:1
	s_nop 0
	v_pk_mul_f32 v[176:177], v[176:177], v[184:185] op_sel_hi:[1,0]
	v_add_f32_dpp v146, v146, v146 row_half_mirror row_mask:0xf bank_mask:0xf bound_ctrl:1
	v_pk_mul_f32 v[178:179], v[178:179], v[184:185] op_sel_hi:[1,0]
	s_waitcnt lgkmcnt(6)
	v_add_f32_dpp v146, v146, v146 row_mirror row_mask:0xf bank_mask:0xf bound_ctrl:1
	v_pk_fma_f32 v[176:177], v[146:147], v[168:169], v[176:177] op_sel_hi:[0,1,1] neg_lo:[1,0,0] neg_hi:[1,0,0]
	v_pk_fma_f32 v[178:179], v[146:147], v[170:171], v[178:179] op_sel_hi:[0,1,1] neg_lo:[1,0,0] neg_hi:[1,0,0]
	v_pk_fma_f32 v[138:139], v[138:139], v[172:173], v[176:177]
	v_pk_fma_f32 v[140:141], v[140:141], v[174:175], v[178:179]
	v_pk_mul_f32 v[144:145], v[138:139], v[186:187]
	v_pk_fma_f32 v[144:145], v[140:141], v[188:189], v[144:145]
	v_add_f32 v146, v144, v145
	ds_read_b128 v[230:233], v10 offset:4608
	ds_read_b128 v[234:237], v10 offset:4864
	ds_read_b128 v[238:241], v10 offset:5120
	ds_read_b128 v[242:245], v10 offset:5376
	ds_read_b128 v[246:249], v10 offset:5632
	ds_read_b32 v250, v11 offset:4608
	v_add_f32_dpp v146, v146, v146 quad_perm:[1,0,3,2] row_mask:0xf bank_mask:0xf bound_ctrl:1
	v_pk_mul_f32 v[180:181], v[138:139], v[180:181]
	v_pk_fma_f32 v[180:181], v[140:141], v[182:183], v[180:181]
	v_add_f32_dpp v146, v146, v146 quad_perm:[2,3,0,1] row_mask:0xf bank_mask:0xf bound_ctrl:1
	v_add_f32 v148, v180, v181
	v_pk_mul_f32 v[198:199], v[198:199], v[206:207] op_sel_hi:[1,0]
	v_add_f32_dpp v146, v146, v146 row_half_mirror row_mask:0xf bank_mask:0xf bound_ctrl:1
	v_pk_mul_f32 v[200:201], v[200:201], v[206:207] op_sel_hi:[1,0]
	s_waitcnt lgkmcnt(6)
	v_add_f32_dpp v146, v146, v146 row_mirror row_mask:0xf bank_mask:0xf bound_ctrl:1
	v_pk_fma_f32 v[198:199], v[146:147], v[190:191], v[198:199] op_sel_hi:[0,1,1] neg_lo:[1,0,0] neg_hi:[1,0,0]
	v_pk_fma_f32 v[200:201], v[146:147], v[192:193], v[200:201] op_sel_hi:[0,1,1] neg_lo:[1,0,0] neg_hi:[1,0,0]
	v_pk_fma_f32 v[138:139], v[138:139], v[194:195], v[198:199]
	v_pk_fma_f32 v[140:141], v[140:141], v[196:197], v[200:201]
	v_pk_mul_f32 v[144:145], v[138:139], v[208:209]
	v_pk_fma_f32 v[144:145], v[140:141], v[210:211], v[144:145]
	v_add_f32 v146, v144, v145
	ds_read_b128 v[164:167], v10 offset:6144
	ds_read_b128 v[168:171], v10 offset:6400
	ds_read_b128 v[172:175], v10 offset:6656
	ds_read_b128 v[176:179], v10 offset:6912
	ds_read_b128 v[180:183], v10 offset:7168
	ds_read_b32 v184, v11 offset:6144
	v_add_f32_dpp v146, v146, v146 quad_perm:[1,0,3,2] row_mask:0xf bank_mask:0xf bound_ctrl:1
	v_pk_mul_f32 v[202:203], v[138:139], v[202:203]
	v_pk_fma_f32 v[202:203], v[140:141], v[204:205], v[202:203]
	v_add_f32_dpp v146, v146, v146 quad_perm:[2,3,0,1] row_mask:0xf bank_mask:0xf bound_ctrl:1
	v_add_f32 v149, v202, v203
	v_pk_mul_f32 v[220:221], v[220:221], v[228:229] op_sel_hi:[1,0]
	v_add_f32_dpp v146, v146, v146 row_half_mirror row_mask:0xf bank_mask:0xf bound_ctrl:1
	v_pk_mul_f32 v[222:223], v[222:223], v[228:229] op_sel_hi:[1,0]
	s_waitcnt lgkmcnt(6)
	v_add_f32_dpp v146, v146, v146 row_mirror row_mask:0xf bank_mask:0xf bound_ctrl:1
	v_pk_fma_f32 v[220:221], v[146:147], v[212:213], v[220:221] op_sel_hi:[0,1,1] neg_lo:[1,0,0] neg_hi:[1,0,0]
	v_pk_fma_f32 v[222:223], v[146:147], v[214:215], v[222:223] op_sel_hi:[0,1,1] neg_lo:[1,0,0] neg_hi:[1,0,0]
	v_pk_fma_f32 v[138:139], v[138:139], v[216:217], v[220:221]
	v_pk_fma_f32 v[140:141], v[140:141], v[218:219], v[222:223]
	v_pk_mul_f32 v[144:145], v[138:139], v[230:231]
	v_pk_fma_f32 v[144:145], v[140:141], v[232:233], v[144:145]
	v_add_f32 v146, v144, v145
	ds_read_b128 v[186:189], v10 offset:7680
	ds_read_b128 v[190:193], v10 offset:7936
	ds_read_b128 v[194:197], v10 offset:8192
	ds_read_b128 v[198:201], v10 offset:8448
	ds_read_b128 v[202:205], v10 offset:8704
	ds_read_b32 v206, v11 offset:7680
	v_add_f32_dpp v146, v146, v146 quad_perm:[1,0,3,2] row_mask:0xf bank_mask:0xf bound_ctrl:1
	v_pk_mul_f32 v[224:225], v[138:139], v[224:225]
	v_pk_fma_f32 v[224:225], v[140:141], v[226:227], v[224:225]
	v_add_f32_dpp v146, v146, v146 quad_perm:[2,3,0,1] row_mask:0xf bank_mask:0xf bound_ctrl:1
	v_add_f32 v150, v224, v225
	v_pk_mul_f32 v[242:243], v[242:243], v[250:251] op_sel_hi:[1,0]
	v_add_f32_dpp v146, v146, v146 row_half_mirror row_mask:0xf bank_mask:0xf bound_ctrl:1
	v_pk_mul_f32 v[244:245], v[244:245], v[250:251] op_sel_hi:[1,0]
	s_waitcnt lgkmcnt(6)
	v_add_f32_dpp v146, v146, v146 row_mirror row_mask:0xf bank_mask:0xf bound_ctrl:1
	v_pk_fma_f32 v[242:243], v[146:147], v[234:235], v[242:243] op_sel_hi:[0,1,1] neg_lo:[1,0,0] neg_hi:[1,0,0]
	v_pk_fma_f32 v[244:245], v[146:147], v[236:237], v[244:245] op_sel_hi:[0,1,1] neg_lo:[1,0,0] neg_hi:[1,0,0]
	v_pk_fma_f32 v[138:139], v[138:139], v[238:239], v[242:243]
	v_pk_fma_f32 v[140:141], v[140:141], v[240:241], v[244:245]
	v_pk_mul_f32 v[144:145], v[138:139], v[164:165]
	v_pk_fma_f32 v[144:145], v[140:141], v[166:167], v[144:145]
	v_add_f32 v146, v144, v145
	ds_read_b128 v[208:211], v10 offset:9216
	ds_read_b128 v[212:215], v10 offset:9472
	ds_read_b128 v[216:219], v10 offset:9728
	ds_read_b128 v[220:223], v10 offset:9984
	ds_read_b128 v[224:227], v10 offset:10240
	ds_read_b32 v228, v11 offset:9216
	v_add_f32_dpp v146, v146, v146 quad_perm:[1,0,3,2] row_mask:0xf bank_mask:0xf bound_ctrl:1
	v_pk_mul_f32 v[246:247], v[138:139], v[246:247]
	v_pk_fma_f32 v[246:247], v[140:141], v[248:249], v[246:247]
	v_add_f32_dpp v146, v146, v146 quad_perm:[2,3,0,1] row_mask:0xf bank_mask:0xf bound_ctrl:1
	v_add_f32 v151, v246, v247
	v_pk_mul_f32 v[176:177], v[176:177], v[184:185] op_sel_hi:[1,0]
	v_add_f32_dpp v146, v146, v146 row_half_mirror row_mask:0xf bank_mask:0xf bound_ctrl:1
	v_pk_mul_f32 v[178:179], v[178:179], v[184:185] op_sel_hi:[1,0]
	s_waitcnt lgkmcnt(6)
	v_add_f32_dpp v146, v146, v146 row_mirror row_mask:0xf bank_mask:0xf bound_ctrl:1
	v_pk_fma_f32 v[176:177], v[146:147], v[168:169], v[176:177] op_sel_hi:[0,1,1] neg_lo:[1,0,0] neg_hi:[1,0,0]
	v_pk_fma_f32 v[178:179], v[146:147], v[170:171], v[178:179] op_sel_hi:[0,1,1] neg_lo:[1,0,0] neg_hi:[1,0,0]
	v_pk_fma_f32 v[138:139], v[138:139], v[172:173], v[176:177]
	v_pk_fma_f32 v[140:141], v[140:141], v[174:175], v[178:179]
	v_pk_mul_f32 v[144:145], v[138:139], v[186:187]
	v_pk_fma_f32 v[144:145], v[140:141], v[188:189], v[144:145]
	v_add_f32 v146, v144, v145
	ds_read_b128 v[230:233], v10 offset:10752
	ds_read_b128 v[234:237], v10 offset:11008
	ds_read_b128 v[238:241], v10 offset:11264
	ds_read_b128 v[242:245], v10 offset:11520
	ds_read_b128 v[246:249], v10 offset:11776
	ds_read_b32 v250, v11 offset:10752
	v_add_f32_dpp v146, v146, v146 quad_perm:[1,0,3,2] row_mask:0xf bank_mask:0xf bound_ctrl:1
	v_pk_mul_f32 v[180:181], v[138:139], v[180:181]
	v_pk_fma_f32 v[180:181], v[140:141], v[182:183], v[180:181]
	v_add_f32_dpp v146, v146, v146 quad_perm:[2,3,0,1] row_mask:0xf bank_mask:0xf bound_ctrl:1
	v_add_f32 v152, v180, v181
	v_pk_mul_f32 v[198:199], v[198:199], v[206:207] op_sel_hi:[1,0]
	v_add_f32_dpp v146, v146, v146 row_half_mirror row_mask:0xf bank_mask:0xf bound_ctrl:1
	v_pk_mul_f32 v[200:201], v[200:201], v[206:207] op_sel_hi:[1,0]
	s_waitcnt lgkmcnt(6)
	v_add_f32_dpp v146, v146, v146 row_mirror row_mask:0xf bank_mask:0xf bound_ctrl:1
	v_pk_fma_f32 v[198:199], v[146:147], v[190:191], v[198:199] op_sel_hi:[0,1,1] neg_lo:[1,0,0] neg_hi:[1,0,0]
	v_pk_fma_f32 v[200:201], v[146:147], v[192:193], v[200:201] op_sel_hi:[0,1,1] neg_lo:[1,0,0] neg_hi:[1,0,0]
	v_pk_fma_f32 v[138:139], v[138:139], v[194:195], v[198:199]
	v_pk_fma_f32 v[140:141], v[140:141], v[196:197], v[200:201]
	v_pk_mul_f32 v[144:145], v[138:139], v[208:209]
	v_pk_fma_f32 v[144:145], v[140:141], v[210:211], v[144:145]
	v_add_f32 v146, v144, v145
	ds_read_b128 v[164:167], v10 offset:12288
	ds_read_b128 v[168:171], v10 offset:12544
	ds_read_b128 v[172:175], v10 offset:12800
	ds_read_b128 v[176:179], v10 offset:13056
	ds_read_b128 v[180:183], v10 offset:13312
	ds_read_b32 v184, v11 offset:12288
	v_add_f32_dpp v146, v146, v146 quad_perm:[1,0,3,2] row_mask:0xf bank_mask:0xf bound_ctrl:1
	v_pk_mul_f32 v[202:203], v[138:139], v[202:203]
	v_pk_fma_f32 v[202:203], v[140:141], v[204:205], v[202:203]
	v_add_f32_dpp v146, v146, v146 quad_perm:[2,3,0,1] row_mask:0xf bank_mask:0xf bound_ctrl:1
	v_add_f32 v153, v202, v203
	v_pk_mul_f32 v[220:221], v[220:221], v[228:229] op_sel_hi:[1,0]
	v_add_f32_dpp v146, v146, v146 row_half_mirror row_mask:0xf bank_mask:0xf bound_ctrl:1
	v_pk_mul_f32 v[222:223], v[222:223], v[228:229] op_sel_hi:[1,0]
	s_waitcnt lgkmcnt(6)
	v_add_f32_dpp v146, v146, v146 row_mirror row_mask:0xf bank_mask:0xf bound_ctrl:1
	v_pk_fma_f32 v[220:221], v[146:147], v[212:213], v[220:221] op_sel_hi:[0,1,1] neg_lo:[1,0,0] neg_hi:[1,0,0]
	v_pk_fma_f32 v[222:223], v[146:147], v[214:215], v[222:223] op_sel_hi:[0,1,1] neg_lo:[1,0,0] neg_hi:[1,0,0]
	v_pk_fma_f32 v[138:139], v[138:139], v[216:217], v[220:221]
	v_pk_fma_f32 v[140:141], v[140:141], v[218:219], v[222:223]
	v_pk_mul_f32 v[144:145], v[138:139], v[230:231]
	v_pk_fma_f32 v[144:145], v[140:141], v[232:233], v[144:145]
	v_add_f32 v146, v144, v145
	ds_read_b128 v[186:189], v10 offset:13824
	ds_read_b128 v[190:193], v10 offset:14080
	ds_read_b128 v[194:197], v10 offset:14336
	ds_read_b128 v[198:201], v10 offset:14592
	ds_read_b128 v[202:205], v10 offset:14848
	ds_read_b32 v206, v11 offset:13824
	v_add_f32_dpp v146, v146, v146 quad_perm:[1,0,3,2] row_mask:0xf bank_mask:0xf bound_ctrl:1
	v_pk_mul_f32 v[224:225], v[138:139], v[224:225]
	v_pk_fma_f32 v[224:225], v[140:141], v[226:227], v[224:225]
	v_add_f32_dpp v146, v146, v146 quad_perm:[2,3,0,1] row_mask:0xf bank_mask:0xf bound_ctrl:1
	v_add_f32 v154, v224, v225
	v_pk_mul_f32 v[242:243], v[242:243], v[250:251] op_sel_hi:[1,0]
	v_add_f32_dpp v146, v146, v146 row_half_mirror row_mask:0xf bank_mask:0xf bound_ctrl:1
	v_pk_mul_f32 v[244:245], v[244:245], v[250:251] op_sel_hi:[1,0]
	s_waitcnt lgkmcnt(6)
	v_add_f32_dpp v146, v146, v146 row_mirror row_mask:0xf bank_mask:0xf bound_ctrl:1
	v_pk_fma_f32 v[242:243], v[146:147], v[234:235], v[242:243] op_sel_hi:[0,1,1] neg_lo:[1,0,0] neg_hi:[1,0,0]
	v_pk_fma_f32 v[244:245], v[146:147], v[236:237], v[244:245] op_sel_hi:[0,1,1] neg_lo:[1,0,0] neg_hi:[1,0,0]
	v_pk_fma_f32 v[138:139], v[138:139], v[238:239], v[242:243]
	v_pk_fma_f32 v[140:141], v[140:141], v[240:241], v[244:245]
	v_pk_mul_f32 v[144:145], v[138:139], v[164:165]
	v_pk_fma_f32 v[144:145], v[140:141], v[166:167], v[144:145]
	v_add_f32 v146, v144, v145
	ds_read_b128 v[208:211], v10 offset:15360
	ds_read_b128 v[212:215], v10 offset:15616
	ds_read_b128 v[216:219], v10 offset:15872
	ds_read_b128 v[220:223], v10 offset:16128
	ds_read_b128 v[224:227], v10 offset:16384
	ds_read_b32 v228, v11 offset:15360
	v_add_f32_dpp v146, v146, v146 quad_perm:[1,0,3,2] row_mask:0xf bank_mask:0xf bound_ctrl:1
	v_pk_mul_f32 v[246:247], v[138:139], v[246:247]
	v_pk_fma_f32 v[246:247], v[140:141], v[248:249], v[246:247]
	v_add_f32_dpp v146, v146, v146 quad_perm:[2,3,0,1] row_mask:0xf bank_mask:0xf bound_ctrl:1
	v_add_f32 v155, v246, v247
	v_pk_mul_f32 v[176:177], v[176:177], v[184:185] op_sel_hi:[1,0]
	v_add_f32_dpp v146, v146, v146 row_half_mirror row_mask:0xf bank_mask:0xf bound_ctrl:1
	v_pk_mul_f32 v[178:179], v[178:179], v[184:185] op_sel_hi:[1,0]
	s_waitcnt lgkmcnt(6)
	v_add_f32_dpp v146, v146, v146 row_mirror row_mask:0xf bank_mask:0xf bound_ctrl:1
	v_pk_fma_f32 v[176:177], v[146:147], v[168:169], v[176:177] op_sel_hi:[0,1,1] neg_lo:[1,0,0] neg_hi:[1,0,0]
	v_pk_fma_f32 v[178:179], v[146:147], v[170:171], v[178:179] op_sel_hi:[0,1,1] neg_lo:[1,0,0] neg_hi:[1,0,0]
	v_pk_fma_f32 v[138:139], v[138:139], v[172:173], v[176:177]
	v_pk_fma_f32 v[140:141], v[140:141], v[174:175], v[178:179]
	v_pk_mul_f32 v[144:145], v[138:139], v[186:187]
	v_pk_fma_f32 v[144:145], v[140:141], v[188:189], v[144:145]
	v_add_f32 v146, v144, v145
	ds_read_b128 v[230:233], v10 offset:16896
	ds_read_b128 v[234:237], v10 offset:17152
	ds_read_b128 v[238:241], v10 offset:17408
	ds_read_b128 v[242:245], v10 offset:17664
	ds_read_b128 v[246:249], v10 offset:17920
	ds_read_b32 v250, v11 offset:16896
	v_add_f32_dpp v146, v146, v146 quad_perm:[1,0,3,2] row_mask:0xf bank_mask:0xf bound_ctrl:1
	v_pk_mul_f32 v[180:181], v[138:139], v[180:181]
	v_pk_fma_f32 v[180:181], v[140:141], v[182:183], v[180:181]
	v_add_f32_dpp v146, v146, v146 quad_perm:[2,3,0,1] row_mask:0xf bank_mask:0xf bound_ctrl:1
	v_add_f32 v156, v180, v181
	v_pk_mul_f32 v[198:199], v[198:199], v[206:207] op_sel_hi:[1,0]
	v_add_f32_dpp v146, v146, v146 row_half_mirror row_mask:0xf bank_mask:0xf bound_ctrl:1
	v_pk_mul_f32 v[200:201], v[200:201], v[206:207] op_sel_hi:[1,0]
	s_waitcnt lgkmcnt(6)
	v_add_f32_dpp v146, v146, v146 row_mirror row_mask:0xf bank_mask:0xf bound_ctrl:1
	v_pk_fma_f32 v[198:199], v[146:147], v[190:191], v[198:199] op_sel_hi:[0,1,1] neg_lo:[1,0,0] neg_hi:[1,0,0]
	v_pk_fma_f32 v[200:201], v[146:147], v[192:193], v[200:201] op_sel_hi:[0,1,1] neg_lo:[1,0,0] neg_hi:[1,0,0]
	v_pk_fma_f32 v[138:139], v[138:139], v[194:195], v[198:199]
	v_pk_fma_f32 v[140:141], v[140:141], v[196:197], v[200:201]
	v_pk_mul_f32 v[144:145], v[138:139], v[208:209]
	v_pk_fma_f32 v[144:145], v[140:141], v[210:211], v[144:145]
	v_add_f32 v146, v144, v145
	ds_read_b128 v[164:167], v10 offset:18432
	ds_read_b128 v[168:171], v10 offset:18688
	ds_read_b128 v[172:175], v10 offset:18944
	ds_read_b128 v[176:179], v10 offset:19200
	ds_read_b128 v[180:183], v10 offset:19456
	ds_read_b32 v184, v11 offset:18432
	v_add_f32_dpp v146, v146, v146 quad_perm:[1,0,3,2] row_mask:0xf bank_mask:0xf bound_ctrl:1
	v_pk_mul_f32 v[202:203], v[138:139], v[202:203]
	v_pk_fma_f32 v[202:203], v[140:141], v[204:205], v[202:203]
	v_add_f32_dpp v146, v146, v146 quad_perm:[2,3,0,1] row_mask:0xf bank_mask:0xf bound_ctrl:1
	v_add_f32 v157, v202, v203
	v_pk_mul_f32 v[220:221], v[220:221], v[228:229] op_sel_hi:[1,0]
	v_add_f32_dpp v146, v146, v146 row_half_mirror row_mask:0xf bank_mask:0xf bound_ctrl:1
	v_pk_mul_f32 v[222:223], v[222:223], v[228:229] op_sel_hi:[1,0]
	s_waitcnt lgkmcnt(6)
	v_add_f32_dpp v146, v146, v146 row_mirror row_mask:0xf bank_mask:0xf bound_ctrl:1
	v_pk_fma_f32 v[220:221], v[146:147], v[212:213], v[220:221] op_sel_hi:[0,1,1] neg_lo:[1,0,0] neg_hi:[1,0,0]
	v_pk_fma_f32 v[222:223], v[146:147], v[214:215], v[222:223] op_sel_hi:[0,1,1] neg_lo:[1,0,0] neg_hi:[1,0,0]
	v_pk_fma_f32 v[138:139], v[138:139], v[216:217], v[220:221]
	v_pk_fma_f32 v[140:141], v[140:141], v[218:219], v[222:223]
	v_pk_mul_f32 v[144:145], v[138:139], v[230:231]
	v_pk_fma_f32 v[144:145], v[140:141], v[232:233], v[144:145]
	v_add_f32 v146, v144, v145
	ds_read_b128 v[186:189], v10 offset:19968
	ds_read_b128 v[190:193], v10 offset:20224
	ds_read_b128 v[194:197], v10 offset:20480
	ds_read_b128 v[198:201], v10 offset:20736
	ds_read_b128 v[202:205], v10 offset:20992
	ds_read_b32 v206, v11 offset:19968
	v_add_f32_dpp v146, v146, v146 quad_perm:[1,0,3,2] row_mask:0xf bank_mask:0xf bound_ctrl:1
	v_pk_mul_f32 v[224:225], v[138:139], v[224:225]
	v_pk_fma_f32 v[224:225], v[140:141], v[226:227], v[224:225]
	v_add_f32_dpp v146, v146, v146 quad_perm:[2,3,0,1] row_mask:0xf bank_mask:0xf bound_ctrl:1
	v_add_f32 v158, v224, v225
	v_pk_mul_f32 v[242:243], v[242:243], v[250:251] op_sel_hi:[1,0]
	v_add_f32_dpp v146, v146, v146 row_half_mirror row_mask:0xf bank_mask:0xf bound_ctrl:1
	v_pk_mul_f32 v[244:245], v[244:245], v[250:251] op_sel_hi:[1,0]
	s_waitcnt lgkmcnt(6)
	v_add_f32_dpp v146, v146, v146 row_mirror row_mask:0xf bank_mask:0xf bound_ctrl:1
	v_pk_fma_f32 v[242:243], v[146:147], v[234:235], v[242:243] op_sel_hi:[0,1,1] neg_lo:[1,0,0] neg_hi:[1,0,0]
	v_pk_fma_f32 v[244:245], v[146:147], v[236:237], v[244:245] op_sel_hi:[0,1,1] neg_lo:[1,0,0] neg_hi:[1,0,0]
	v_pk_fma_f32 v[138:139], v[138:139], v[238:239], v[242:243]
	v_pk_fma_f32 v[140:141], v[140:141], v[240:241], v[244:245]
	v_pk_mul_f32 v[144:145], v[138:139], v[164:165]
	v_pk_fma_f32 v[144:145], v[140:141], v[166:167], v[144:145]
	v_add_f32 v146, v144, v145
	ds_read_b128 v[208:211], v10 offset:21504
	ds_read_b128 v[212:215], v10 offset:21760
	ds_read_b128 v[216:219], v10 offset:22016
	ds_read_b128 v[220:223], v10 offset:22272
	ds_read_b128 v[224:227], v10 offset:22528
	ds_read_b32 v228, v11 offset:21504
	v_add_f32_dpp v146, v146, v146 quad_perm:[1,0,3,2] row_mask:0xf bank_mask:0xf bound_ctrl:1
	v_pk_mul_f32 v[246:247], v[138:139], v[246:247]
	v_pk_fma_f32 v[246:247], v[140:141], v[248:249], v[246:247]
	v_add_f32_dpp v146, v146, v146 quad_perm:[2,3,0,1] row_mask:0xf bank_mask:0xf bound_ctrl:1
	v_add_f32 v159, v246, v247
	v_pk_mul_f32 v[176:177], v[176:177], v[184:185] op_sel_hi:[1,0]
	v_add_f32_dpp v146, v146, v146 row_half_mirror row_mask:0xf bank_mask:0xf bound_ctrl:1
	v_pk_mul_f32 v[178:179], v[178:179], v[184:185] op_sel_hi:[1,0]
	s_waitcnt lgkmcnt(6)
	v_add_f32_dpp v146, v146, v146 row_mirror row_mask:0xf bank_mask:0xf bound_ctrl:1
	v_pk_fma_f32 v[176:177], v[146:147], v[168:169], v[176:177] op_sel_hi:[0,1,1] neg_lo:[1,0,0] neg_hi:[1,0,0]
	v_pk_fma_f32 v[178:179], v[146:147], v[170:171], v[178:179] op_sel_hi:[0,1,1] neg_lo:[1,0,0] neg_hi:[1,0,0]
	v_pk_fma_f32 v[138:139], v[138:139], v[172:173], v[176:177]
	v_pk_fma_f32 v[140:141], v[140:141], v[174:175], v[178:179]
	v_pk_mul_f32 v[144:145], v[138:139], v[186:187]
	v_pk_fma_f32 v[144:145], v[140:141], v[188:189], v[144:145]
	v_add_f32 v146, v144, v145
	ds_read_b128 v[230:233], v10 offset:23040
	ds_read_b128 v[234:237], v10 offset:23296
	ds_read_b128 v[238:241], v10 offset:23552
	ds_read_b128 v[242:245], v10 offset:23808
	ds_read_b128 v[246:249], v10 offset:24064
	ds_read_b32 v250, v11 offset:23040
	v_add_f32_dpp v146, v146, v146 quad_perm:[1,0,3,2] row_mask:0xf bank_mask:0xf bound_ctrl:1
	v_pk_mul_f32 v[180:181], v[138:139], v[180:181]
	v_pk_fma_f32 v[180:181], v[140:141], v[182:183], v[180:181]
	v_add_f32_dpp v146, v146, v146 quad_perm:[2,3,0,1] row_mask:0xf bank_mask:0xf bound_ctrl:1
	v_add_f32 v160, v180, v181
	v_pk_mul_f32 v[198:199], v[198:199], v[206:207] op_sel_hi:[1,0]
	v_add_f32_dpp v146, v146, v146 row_half_mirror row_mask:0xf bank_mask:0xf bound_ctrl:1
	v_pk_mul_f32 v[200:201], v[200:201], v[206:207] op_sel_hi:[1,0]
	s_waitcnt lgkmcnt(6)
	v_add_f32_dpp v146, v146, v146 row_mirror row_mask:0xf bank_mask:0xf bound_ctrl:1
	v_pk_fma_f32 v[198:199], v[146:147], v[190:191], v[198:199] op_sel_hi:[0,1,1] neg_lo:[1,0,0] neg_hi:[1,0,0]
	v_pk_fma_f32 v[200:201], v[146:147], v[192:193], v[200:201] op_sel_hi:[0,1,1] neg_lo:[1,0,0] neg_hi:[1,0,0]
	v_pk_fma_f32 v[138:139], v[138:139], v[194:195], v[198:199]
	v_pk_fma_f32 v[140:141], v[140:141], v[196:197], v[200:201]
	v_pk_mul_f32 v[144:145], v[138:139], v[208:209]
	v_pk_fma_f32 v[144:145], v[140:141], v[210:211], v[144:145]
	v_add_f32 v146, v144, v145
	ds_read_b128 v[164:167], v10 offset:24576
	ds_read_b128 v[168:171], v10 offset:24832
	ds_read_b128 v[172:175], v10 offset:25088
	ds_read_b128 v[176:179], v10 offset:25344
	ds_read_b128 v[180:183], v10 offset:25600
	ds_read_b32 v184, v11 offset:24576
	v_add_f32_dpp v146, v146, v146 quad_perm:[1,0,3,2] row_mask:0xf bank_mask:0xf bound_ctrl:1
	v_pk_mul_f32 v[202:203], v[138:139], v[202:203]
	v_pk_fma_f32 v[202:203], v[140:141], v[204:205], v[202:203]
	v_add_f32_dpp v146, v146, v146 quad_perm:[2,3,0,1] row_mask:0xf bank_mask:0xf bound_ctrl:1
	v_add_f32 v161, v202, v203
	v_pk_mul_f32 v[220:221], v[220:221], v[228:229] op_sel_hi:[1,0]
	v_add_f32_dpp v146, v146, v146 row_half_mirror row_mask:0xf bank_mask:0xf bound_ctrl:1
	v_pk_mul_f32 v[222:223], v[222:223], v[228:229] op_sel_hi:[1,0]
	s_waitcnt lgkmcnt(6)
	v_add_f32_dpp v146, v146, v146 row_mirror row_mask:0xf bank_mask:0xf bound_ctrl:1
	v_pk_fma_f32 v[220:221], v[146:147], v[212:213], v[220:221] op_sel_hi:[0,1,1] neg_lo:[1,0,0] neg_hi:[1,0,0]
	v_pk_fma_f32 v[222:223], v[146:147], v[214:215], v[222:223] op_sel_hi:[0,1,1] neg_lo:[1,0,0] neg_hi:[1,0,0]
	v_pk_fma_f32 v[138:139], v[138:139], v[216:217], v[220:221]
	v_pk_fma_f32 v[140:141], v[140:141], v[218:219], v[222:223]
	v_pk_mul_f32 v[144:145], v[138:139], v[230:231]
	v_pk_fma_f32 v[144:145], v[140:141], v[232:233], v[144:145]
	v_add_f32 v146, v144, v145
	ds_read_b128 v[186:189], v10 offset:26112
	ds_read_b128 v[190:193], v10 offset:26368
	ds_read_b128 v[194:197], v10 offset:26624
	ds_read_b128 v[198:201], v10 offset:26880
	ds_read_b128 v[202:205], v10 offset:27136
	ds_read_b32 v206, v11 offset:26112
	v_add_f32_dpp v146, v146, v146 quad_perm:[1,0,3,2] row_mask:0xf bank_mask:0xf bound_ctrl:1
	v_pk_mul_f32 v[224:225], v[138:139], v[224:225]
	v_pk_fma_f32 v[224:225], v[140:141], v[226:227], v[224:225]
	v_add_f32_dpp v146, v146, v146 quad_perm:[2,3,0,1] row_mask:0xf bank_mask:0xf bound_ctrl:1
	v_add_f32 v162, v224, v225
	v_pk_mul_f32 v[242:243], v[242:243], v[250:251] op_sel_hi:[1,0]
	v_add_f32_dpp v146, v146, v146 row_half_mirror row_mask:0xf bank_mask:0xf bound_ctrl:1
	v_pk_mul_f32 v[244:245], v[244:245], v[250:251] op_sel_hi:[1,0]
	s_waitcnt lgkmcnt(6)
	v_add_f32_dpp v146, v146, v146 row_mirror row_mask:0xf bank_mask:0xf bound_ctrl:1
	v_pk_fma_f32 v[242:243], v[146:147], v[234:235], v[242:243] op_sel_hi:[0,1,1] neg_lo:[1,0,0] neg_hi:[1,0,0]
	v_pk_fma_f32 v[244:245], v[146:147], v[236:237], v[244:245] op_sel_hi:[0,1,1] neg_lo:[1,0,0] neg_hi:[1,0,0]
	v_pk_fma_f32 v[138:139], v[138:139], v[238:239], v[242:243]
	v_pk_fma_f32 v[140:141], v[140:141], v[240:241], v[244:245]
	v_pk_mul_f32 v[144:145], v[138:139], v[164:165]
	v_pk_fma_f32 v[144:145], v[140:141], v[166:167], v[144:145]
	v_add_f32 v146, v144, v145
	ds_read_b128 v[208:211], v10 offset:27648
	ds_read_b128 v[212:215], v10 offset:27904
	ds_read_b128 v[216:219], v10 offset:28160
	ds_read_b128 v[220:223], v10 offset:28416
	ds_read_b128 v[224:227], v10 offset:28672
	ds_read_b32 v228, v11 offset:27648
	v_add_f32_dpp v146, v146, v146 quad_perm:[1,0,3,2] row_mask:0xf bank_mask:0xf bound_ctrl:1
	v_pk_mul_f32 v[246:247], v[138:139], v[246:247]
	v_pk_fma_f32 v[246:247], v[140:141], v[248:249], v[246:247]
	v_add_f32_dpp v146, v146, v146 quad_perm:[2,3,0,1] row_mask:0xf bank_mask:0xf bound_ctrl:1
	v_add_f32 v163, v246, v247
	v_pk_mul_f32 v[176:177], v[176:177], v[184:185] op_sel_hi:[1,0]
	v_add_f32_dpp v146, v146, v146 row_half_mirror row_mask:0xf bank_mask:0xf bound_ctrl:1
	v_pk_mul_f32 v[178:179], v[178:179], v[184:185] op_sel_hi:[1,0]
	s_waitcnt lgkmcnt(6)
	v_add_f32_dpp v146, v146, v146 row_mirror row_mask:0xf bank_mask:0xf bound_ctrl:1
	v_pk_fma_f32 v[176:177], v[146:147], v[168:169], v[176:177] op_sel_hi:[0,1,1] neg_lo:[1,0,0] neg_hi:[1,0,0]
	v_pk_fma_f32 v[178:179], v[146:147], v[170:171], v[178:179] op_sel_hi:[0,1,1] neg_lo:[1,0,0] neg_hi:[1,0,0]
	v_pk_fma_f32 v[138:139], v[138:139], v[172:173], v[176:177]
	v_pk_fma_f32 v[140:141], v[140:141], v[174:175], v[178:179]
	v_pk_mul_f32 v[144:145], v[138:139], v[186:187]
	v_pk_fma_f32 v[144:145], v[140:141], v[188:189], v[144:145]
	v_add_f32 v146, v144, v145
	v_add_f32_dpp v230, v148, v148 row_mirror row_mask:0xf bank_mask:0x3 bound_ctrl:1
	v_add_f32_dpp v230, v156, v156 row_mirror row_mask:0xf bank_mask:0xc bound_ctrl:1
	v_add_f32_dpp v231, v149, v149 row_mirror row_mask:0xf bank_mask:0x3 bound_ctrl:1
	v_add_f32_dpp v231, v157, v157 row_mirror row_mask:0xf bank_mask:0xc bound_ctrl:1
	v_add_f32_dpp v232, v150, v150 row_mirror row_mask:0xf bank_mask:0x3 bound_ctrl:1
	v_add_f32_dpp v232, v158, v158 row_mirror row_mask:0xf bank_mask:0xc bound_ctrl:1
	v_add_f32_dpp v233, v151, v151 row_mirror row_mask:0xf bank_mask:0x3 bound_ctrl:1
	v_add_f32_dpp v233, v159, v159 row_mirror row_mask:0xf bank_mask:0xc bound_ctrl:1
	v_add_f32_dpp v234, v152, v152 row_mirror row_mask:0xf bank_mask:0x3 bound_ctrl:1
	v_add_f32_dpp v234, v160, v160 row_mirror row_mask:0xf bank_mask:0xc bound_ctrl:1
	v_add_f32_dpp v235, v153, v153 row_mirror row_mask:0xf bank_mask:0x3 bound_ctrl:1
	v_add_f32_dpp v235, v161, v161 row_mirror row_mask:0xf bank_mask:0xc bound_ctrl:1
	v_add_f32_dpp v236, v154, v154 row_mirror row_mask:0xf bank_mask:0x3 bound_ctrl:1
	v_add_f32_dpp v236, v162, v162 row_mirror row_mask:0xf bank_mask:0xc bound_ctrl:1
	v_add_f32_dpp v237, v155, v155 row_mirror row_mask:0xf bank_mask:0x3 bound_ctrl:1
	v_add_f32_dpp v237, v163, v163 row_mirror row_mask:0xf bank_mask:0xc bound_ctrl:1
	v_add_f32_dpp v238, v230, v230 row_half_mirror row_mask:0xf bank_mask:0x5 bound_ctrl:1
	v_add_f32_dpp v238, v234, v234 row_half_mirror row_mask:0xf bank_mask:0xa bound_ctrl:1
	v_add_f32_dpp v239, v231, v231 row_half_mirror row_mask:0xf bank_mask:0x5 bound_ctrl:1
	v_add_f32_dpp v239, v235, v235 row_half_mirror row_mask:0xf bank_mask:0xa bound_ctrl:1
	v_add_f32_dpp v240, v232, v232 row_half_mirror row_mask:0xf bank_mask:0x5 bound_ctrl:1
	v_add_f32_dpp v240, v236, v236 row_half_mirror row_mask:0xf bank_mask:0xa bound_ctrl:1
	v_add_f32_dpp v241, v233, v233 row_half_mirror row_mask:0xf bank_mask:0x5 bound_ctrl:1
	v_add_f32_dpp v241, v237, v237 row_half_mirror row_mask:0xf bank_mask:0xa bound_ctrl:1
	s_mov_b32 vcc_lo, 0xcccccccc
	s_mov_b32 vcc_hi, 0xcccccccc
	v_cndmask_b32 v244, v240, v238, vcc
	v_cndmask_b32 v245, v241, v239, vcc
	v_cndmask_b32 v242, v238, v240, vcc
	v_cndmask_b32 v243, v239, v241, vcc
	v_add_f32_dpp v242, v244, v242 quad_perm:[2,3,0,1] row_mask:0xf bank_mask:0xf bound_ctrl:1
	v_add_f32_dpp v243, v245, v243 quad_perm:[2,3,0,1] row_mask:0xf bank_mask:0xf bound_ctrl:1
	s_mov_b32 vcc_lo, 0xaaaaaaaa
	s_mov_b32 vcc_hi, 0xaaaaaaaa
	v_cndmask_b32 v244, v243, v242, vcc
	v_cndmask_b32 v245, v242, v243, vcc
	s_nop 0
	v_add_f32_dpp v18, v244, v245 quad_perm:[1,0,3,2] row_mask:0xf bank_mask:0xf bound_ctrl:1
	ds_read_b128 v[230:233], v10 offset:29184
	ds_read_b128 v[234:237], v10 offset:29440
	ds_read_b128 v[238:241], v10 offset:29696
	ds_read_b128 v[242:245], v10 offset:29952
	ds_read_b128 v[246:249], v10 offset:30208
	ds_read_b32 v250, v11 offset:29184
	v_add_f32_dpp v146, v146, v146 quad_perm:[1,0,3,2] row_mask:0xf bank_mask:0xf bound_ctrl:1
	v_pk_mul_f32 v[180:181], v[138:139], v[180:181]
	v_pk_fma_f32 v[180:181], v[140:141], v[182:183], v[180:181]
	v_add_f32_dpp v146, v146, v146 quad_perm:[2,3,0,1] row_mask:0xf bank_mask:0xf bound_ctrl:1
	v_add_f32 v148, v180, v181
	v_pk_mul_f32 v[198:199], v[198:199], v[206:207] op_sel_hi:[1,0]
	v_add_f32_dpp v146, v146, v146 row_half_mirror row_mask:0xf bank_mask:0xf bound_ctrl:1
	v_pk_mul_f32 v[200:201], v[200:201], v[206:207] op_sel_hi:[1,0]
	s_waitcnt lgkmcnt(6)
	v_add_f32_dpp v146, v146, v146 row_mirror row_mask:0xf bank_mask:0xf bound_ctrl:1
	v_pk_fma_f32 v[198:199], v[146:147], v[190:191], v[198:199] op_sel_hi:[0,1,1] neg_lo:[1,0,0] neg_hi:[1,0,0]
	v_pk_fma_f32 v[200:201], v[146:147], v[192:193], v[200:201] op_sel_hi:[0,1,1] neg_lo:[1,0,0] neg_hi:[1,0,0]
	v_pk_fma_f32 v[138:139], v[138:139], v[194:195], v[198:199]
	v_pk_fma_f32 v[140:141], v[140:141], v[196:197], v[200:201]
	v_pk_mul_f32 v[144:145], v[138:139], v[208:209]
	v_pk_fma_f32 v[144:145], v[140:141], v[210:211], v[144:145]
	v_add_f32 v146, v144, v145
	ds_read_b128 v[164:167], v10 offset:30720
	ds_read_b128 v[168:171], v10 offset:30976
	ds_read_b128 v[172:175], v10 offset:31232
	ds_read_b128 v[176:179], v10 offset:31488
	ds_read_b128 v[180:183], v10 offset:31744
	ds_read_b32 v184, v11 offset:30720
	v_add_f32_dpp v146, v146, v146 quad_perm:[1,0,3,2] row_mask:0xf bank_mask:0xf bound_ctrl:1
	v_pk_mul_f32 v[202:203], v[138:139], v[202:203]
	v_pk_fma_f32 v[202:203], v[140:141], v[204:205], v[202:203]
	v_add_f32_dpp v146, v146, v146 quad_perm:[2,3,0,1] row_mask:0xf bank_mask:0xf bound_ctrl:1
	v_add_f32 v149, v202, v203
	v_pk_mul_f32 v[220:221], v[220:221], v[228:229] op_sel_hi:[1,0]
	v_add_f32_dpp v146, v146, v146 row_half_mirror row_mask:0xf bank_mask:0xf bound_ctrl:1
	v_pk_mul_f32 v[222:223], v[222:223], v[228:229] op_sel_hi:[1,0]
	s_waitcnt lgkmcnt(6)
	v_add_f32_dpp v146, v146, v146 row_mirror row_mask:0xf bank_mask:0xf bound_ctrl:1
	v_pk_fma_f32 v[220:221], v[146:147], v[212:213], v[220:221] op_sel_hi:[0,1,1] neg_lo:[1,0,0] neg_hi:[1,0,0]
	v_pk_fma_f32 v[222:223], v[146:147], v[214:215], v[222:223] op_sel_hi:[0,1,1] neg_lo:[1,0,0] neg_hi:[1,0,0]
	v_pk_fma_f32 v[138:139], v[138:139], v[216:217], v[220:221]
	v_pk_fma_f32 v[140:141], v[140:141], v[218:219], v[222:223]
	v_pk_mul_f32 v[144:145], v[138:139], v[230:231]
	v_pk_fma_f32 v[144:145], v[140:141], v[232:233], v[144:145]
	v_add_f32 v146, v144, v145
	ds_read_b128 v[186:189], v10 offset:32256
	ds_read_b128 v[190:193], v10 offset:32512
	ds_read_b128 v[194:197], v10 offset:32768
	ds_read_b128 v[198:201], v10 offset:33024
	ds_read_b128 v[202:205], v10 offset:33280
	ds_read_b32 v206, v11 offset:32256
	v_add_f32_dpp v146, v146, v146 quad_perm:[1,0,3,2] row_mask:0xf bank_mask:0xf bound_ctrl:1
	v_pk_mul_f32 v[224:225], v[138:139], v[224:225]
	v_pk_fma_f32 v[224:225], v[140:141], v[226:227], v[224:225]
	v_add_f32_dpp v146, v146, v146 quad_perm:[2,3,0,1] row_mask:0xf bank_mask:0xf bound_ctrl:1
	v_add_f32 v150, v224, v225
	v_pk_mul_f32 v[242:243], v[242:243], v[250:251] op_sel_hi:[1,0]
	v_add_f32_dpp v146, v146, v146 row_half_mirror row_mask:0xf bank_mask:0xf bound_ctrl:1
	v_pk_mul_f32 v[244:245], v[244:245], v[250:251] op_sel_hi:[1,0]
	s_waitcnt lgkmcnt(6)
	v_add_f32_dpp v146, v146, v146 row_mirror row_mask:0xf bank_mask:0xf bound_ctrl:1
	v_pk_fma_f32 v[242:243], v[146:147], v[234:235], v[242:243] op_sel_hi:[0,1,1] neg_lo:[1,0,0] neg_hi:[1,0,0]
	v_pk_fma_f32 v[244:245], v[146:147], v[236:237], v[244:245] op_sel_hi:[0,1,1] neg_lo:[1,0,0] neg_hi:[1,0,0]
	v_pk_fma_f32 v[138:139], v[138:139], v[238:239], v[242:243]
	v_pk_fma_f32 v[140:141], v[140:141], v[240:241], v[244:245]
	v_pk_mul_f32 v[144:145], v[138:139], v[164:165]
	v_pk_fma_f32 v[144:145], v[140:141], v[166:167], v[144:145]
	v_add_f32 v146, v144, v145
	ds_read_b128 v[208:211], v10 offset:33792
	ds_read_b128 v[212:215], v10 offset:34048
	ds_read_b128 v[216:219], v10 offset:34304
	ds_read_b128 v[220:223], v10 offset:34560
	ds_read_b128 v[224:227], v10 offset:34816
	ds_read_b32 v228, v11 offset:33792
	v_add_f32_dpp v146, v146, v146 quad_perm:[1,0,3,2] row_mask:0xf bank_mask:0xf bound_ctrl:1
	v_pk_mul_f32 v[246:247], v[138:139], v[246:247]
	v_pk_fma_f32 v[246:247], v[140:141], v[248:249], v[246:247]
	v_add_f32_dpp v146, v146, v146 quad_perm:[2,3,0,1] row_mask:0xf bank_mask:0xf bound_ctrl:1
	v_add_f32 v151, v246, v247
	v_pk_mul_f32 v[176:177], v[176:177], v[184:185] op_sel_hi:[1,0]
	v_add_f32_dpp v146, v146, v146 row_half_mirror row_mask:0xf bank_mask:0xf bound_ctrl:1
	v_pk_mul_f32 v[178:179], v[178:179], v[184:185] op_sel_hi:[1,0]
	s_waitcnt lgkmcnt(6)
	v_add_f32_dpp v146, v146, v146 row_mirror row_mask:0xf bank_mask:0xf bound_ctrl:1
	v_pk_fma_f32 v[176:177], v[146:147], v[168:169], v[176:177] op_sel_hi:[0,1,1] neg_lo:[1,0,0] neg_hi:[1,0,0]
	v_pk_fma_f32 v[178:179], v[146:147], v[170:171], v[178:179] op_sel_hi:[0,1,1] neg_lo:[1,0,0] neg_hi:[1,0,0]
	v_pk_fma_f32 v[138:139], v[138:139], v[172:173], v[176:177]
	v_pk_fma_f32 v[140:141], v[140:141], v[174:175], v[178:179]
	v_pk_mul_f32 v[144:145], v[138:139], v[186:187]
	v_pk_fma_f32 v[144:145], v[140:141], v[188:189], v[144:145]
	v_add_f32 v146, v144, v145
	ds_read_b128 v[230:233], v10 offset:35328
	ds_read_b128 v[234:237], v10 offset:35584
	ds_read_b128 v[238:241], v10 offset:35840
	ds_read_b128 v[242:245], v10 offset:36096
	ds_read_b128 v[246:249], v10 offset:36352
	ds_read_b32 v250, v11 offset:35328
	v_add_f32_dpp v146, v146, v146 quad_perm:[1,0,3,2] row_mask:0xf bank_mask:0xf bound_ctrl:1
	v_pk_mul_f32 v[180:181], v[138:139], v[180:181]
	v_pk_fma_f32 v[180:181], v[140:141], v[182:183], v[180:181]
	v_add_f32_dpp v146, v146, v146 quad_perm:[2,3,0,1] row_mask:0xf bank_mask:0xf bound_ctrl:1
	v_add_f32 v152, v180, v181
	v_pk_mul_f32 v[198:199], v[198:199], v[206:207] op_sel_hi:[1,0]
	v_add_f32_dpp v146, v146, v146 row_half_mirror row_mask:0xf bank_mask:0xf bound_ctrl:1
	v_pk_mul_f32 v[200:201], v[200:201], v[206:207] op_sel_hi:[1,0]
	s_waitcnt lgkmcnt(6)
	v_add_f32_dpp v146, v146, v146 row_mirror row_mask:0xf bank_mask:0xf bound_ctrl:1
	v_pk_fma_f32 v[198:199], v[146:147], v[190:191], v[198:199] op_sel_hi:[0,1,1] neg_lo:[1,0,0] neg_hi:[1,0,0]
	v_pk_fma_f32 v[200:201], v[146:147], v[192:193], v[200:201] op_sel_hi:[0,1,1] neg_lo:[1,0,0] neg_hi:[1,0,0]
	v_pk_fma_f32 v[138:139], v[138:139], v[194:195], v[198:199]
	v_pk_fma_f32 v[140:141], v[140:141], v[196:197], v[200:201]
	v_pk_mul_f32 v[144:145], v[138:139], v[208:209]
	v_pk_fma_f32 v[144:145], v[140:141], v[210:211], v[144:145]
	v_add_f32 v146, v144, v145
	ds_read_b128 v[164:167], v10 offset:36864
	ds_read_b128 v[168:171], v10 offset:37120
	ds_read_b128 v[172:175], v10 offset:37376
	ds_read_b128 v[176:179], v10 offset:37632
	ds_read_b128 v[180:183], v10 offset:37888
	ds_read_b32 v184, v11 offset:36864
	v_add_f32_dpp v146, v146, v146 quad_perm:[1,0,3,2] row_mask:0xf bank_mask:0xf bound_ctrl:1
	v_pk_mul_f32 v[202:203], v[138:139], v[202:203]
	v_pk_fma_f32 v[202:203], v[140:141], v[204:205], v[202:203]
	v_add_f32_dpp v146, v146, v146 quad_perm:[2,3,0,1] row_mask:0xf bank_mask:0xf bound_ctrl:1
	v_add_f32 v153, v202, v203
	v_pk_mul_f32 v[220:221], v[220:221], v[228:229] op_sel_hi:[1,0]
	v_add_f32_dpp v146, v146, v146 row_half_mirror row_mask:0xf bank_mask:0xf bound_ctrl:1
	v_pk_mul_f32 v[222:223], v[222:223], v[228:229] op_sel_hi:[1,0]
	s_waitcnt lgkmcnt(6)
	v_add_f32_dpp v146, v146, v146 row_mirror row_mask:0xf bank_mask:0xf bound_ctrl:1
	v_pk_fma_f32 v[220:221], v[146:147], v[212:213], v[220:221] op_sel_hi:[0,1,1] neg_lo:[1,0,0] neg_hi:[1,0,0]
	v_pk_fma_f32 v[222:223], v[146:147], v[214:215], v[222:223] op_sel_hi:[0,1,1] neg_lo:[1,0,0] neg_hi:[1,0,0]
	v_pk_fma_f32 v[138:139], v[138:139], v[216:217], v[220:221]
	v_pk_fma_f32 v[140:141], v[140:141], v[218:219], v[222:223]
	v_pk_mul_f32 v[144:145], v[138:139], v[230:231]
	v_pk_fma_f32 v[144:145], v[140:141], v[232:233], v[144:145]
	v_add_f32 v146, v144, v145
	ds_read_b128 v[186:189], v10 offset:38400
	ds_read_b128 v[190:193], v10 offset:38656
	ds_read_b128 v[194:197], v10 offset:38912
	ds_read_b128 v[198:201], v10 offset:39168
	ds_read_b128 v[202:205], v10 offset:39424
	ds_read_b32 v206, v11 offset:38400
	v_add_f32_dpp v146, v146, v146 quad_perm:[1,0,3,2] row_mask:0xf bank_mask:0xf bound_ctrl:1
	v_pk_mul_f32 v[224:225], v[138:139], v[224:225]
	v_pk_fma_f32 v[224:225], v[140:141], v[226:227], v[224:225]
	v_add_f32_dpp v146, v146, v146 quad_perm:[2,3,0,1] row_mask:0xf bank_mask:0xf bound_ctrl:1
	v_add_f32 v154, v224, v225
	v_pk_mul_f32 v[242:243], v[242:243], v[250:251] op_sel_hi:[1,0]
	v_add_f32_dpp v146, v146, v146 row_half_mirror row_mask:0xf bank_mask:0xf bound_ctrl:1
	v_pk_mul_f32 v[244:245], v[244:245], v[250:251] op_sel_hi:[1,0]
	s_waitcnt lgkmcnt(6)
	v_add_f32_dpp v146, v146, v146 row_mirror row_mask:0xf bank_mask:0xf bound_ctrl:1
	v_pk_fma_f32 v[242:243], v[146:147], v[234:235], v[242:243] op_sel_hi:[0,1,1] neg_lo:[1,0,0] neg_hi:[1,0,0]
	v_pk_fma_f32 v[244:245], v[146:147], v[236:237], v[244:245] op_sel_hi:[0,1,1] neg_lo:[1,0,0] neg_hi:[1,0,0]
	v_pk_fma_f32 v[138:139], v[138:139], v[238:239], v[242:243]
	v_pk_fma_f32 v[140:141], v[140:141], v[240:241], v[244:245]
	v_pk_mul_f32 v[144:145], v[138:139], v[164:165]
	v_pk_fma_f32 v[144:145], v[140:141], v[166:167], v[144:145]
	v_add_f32 v146, v144, v145
	ds_read_b128 v[208:211], v10 offset:39936
	ds_read_b128 v[212:215], v10 offset:40192
	ds_read_b128 v[216:219], v10 offset:40448
	ds_read_b128 v[220:223], v10 offset:40704
	ds_read_b128 v[224:227], v10 offset:40960
	ds_read_b32 v228, v11 offset:39936
	v_add_f32_dpp v146, v146, v146 quad_perm:[1,0,3,2] row_mask:0xf bank_mask:0xf bound_ctrl:1
	v_pk_mul_f32 v[246:247], v[138:139], v[246:247]
	v_pk_fma_f32 v[246:247], v[140:141], v[248:249], v[246:247]
	v_add_f32_dpp v146, v146, v146 quad_perm:[2,3,0,1] row_mask:0xf bank_mask:0xf bound_ctrl:1
	v_add_f32 v155, v246, v247
	v_pk_mul_f32 v[176:177], v[176:177], v[184:185] op_sel_hi:[1,0]
	v_add_f32_dpp v146, v146, v146 row_half_mirror row_mask:0xf bank_mask:0xf bound_ctrl:1
	v_pk_mul_f32 v[178:179], v[178:179], v[184:185] op_sel_hi:[1,0]
	s_waitcnt lgkmcnt(6)
	v_add_f32_dpp v146, v146, v146 row_mirror row_mask:0xf bank_mask:0xf bound_ctrl:1
	v_pk_fma_f32 v[176:177], v[146:147], v[168:169], v[176:177] op_sel_hi:[0,1,1] neg_lo:[1,0,0] neg_hi:[1,0,0]
	v_pk_fma_f32 v[178:179], v[146:147], v[170:171], v[178:179] op_sel_hi:[0,1,1] neg_lo:[1,0,0] neg_hi:[1,0,0]
	v_pk_fma_f32 v[138:139], v[138:139], v[172:173], v[176:177]
	v_pk_fma_f32 v[140:141], v[140:141], v[174:175], v[178:179]
	v_pk_mul_f32 v[144:145], v[138:139], v[186:187]
	v_pk_fma_f32 v[144:145], v[140:141], v[188:189], v[144:145]
	v_add_f32 v146, v144, v145
	ds_read_b128 v[230:233], v10 offset:41472
	ds_read_b128 v[234:237], v10 offset:41728
	ds_read_b128 v[238:241], v10 offset:41984
	ds_read_b128 v[242:245], v10 offset:42240
	ds_read_b128 v[246:249], v10 offset:42496
	ds_read_b32 v250, v11 offset:41472
	v_add_f32_dpp v146, v146, v146 quad_perm:[1,0,3,2] row_mask:0xf bank_mask:0xf bound_ctrl:1
	v_pk_mul_f32 v[180:181], v[138:139], v[180:181]
	v_pk_fma_f32 v[180:181], v[140:141], v[182:183], v[180:181]
	v_add_f32_dpp v146, v146, v146 quad_perm:[2,3,0,1] row_mask:0xf bank_mask:0xf bound_ctrl:1
	v_add_f32 v156, v180, v181
	v_pk_mul_f32 v[198:199], v[198:199], v[206:207] op_sel_hi:[1,0]
	v_add_f32_dpp v146, v146, v146 row_half_mirror row_mask:0xf bank_mask:0xf bound_ctrl:1
	v_pk_mul_f32 v[200:201], v[200:201], v[206:207] op_sel_hi:[1,0]
	s_waitcnt lgkmcnt(6)
	v_add_f32_dpp v146, v146, v146 row_mirror row_mask:0xf bank_mask:0xf bound_ctrl:1
	v_pk_fma_f32 v[198:199], v[146:147], v[190:191], v[198:199] op_sel_hi:[0,1,1] neg_lo:[1,0,0] neg_hi:[1,0,0]
	v_pk_fma_f32 v[200:201], v[146:147], v[192:193], v[200:201] op_sel_hi:[0,1,1] neg_lo:[1,0,0] neg_hi:[1,0,0]
	v_pk_fma_f32 v[138:139], v[138:139], v[194:195], v[198:199]
	v_pk_fma_f32 v[140:141], v[140:141], v[196:197], v[200:201]
	v_pk_mul_f32 v[144:145], v[138:139], v[208:209]
	v_pk_fma_f32 v[144:145], v[140:141], v[210:211], v[144:145]
	v_add_f32 v146, v144, v145
	ds_read_b128 v[164:167], v10 offset:43008
	ds_read_b128 v[168:171], v10 offset:43264
	ds_read_b128 v[172:175], v10 offset:43520
	ds_read_b128 v[176:179], v10 offset:43776
	ds_read_b128 v[180:183], v10 offset:44032
	ds_read_b32 v184, v11 offset:43008
	v_add_f32_dpp v146, v146, v146 quad_perm:[1,0,3,2] row_mask:0xf bank_mask:0xf bound_ctrl:1
	v_pk_mul_f32 v[202:203], v[138:139], v[202:203]
	v_pk_fma_f32 v[202:203], v[140:141], v[204:205], v[202:203]
	v_add_f32_dpp v146, v146, v146 quad_perm:[2,3,0,1] row_mask:0xf bank_mask:0xf bound_ctrl:1
	v_add_f32 v157, v202, v203
	v_pk_mul_f32 v[220:221], v[220:221], v[228:229] op_sel_hi:[1,0]
	v_add_f32_dpp v146, v146, v146 row_half_mirror row_mask:0xf bank_mask:0xf bound_ctrl:1
	v_pk_mul_f32 v[222:223], v[222:223], v[228:229] op_sel_hi:[1,0]
	s_waitcnt lgkmcnt(6)
	v_add_f32_dpp v146, v146, v146 row_mirror row_mask:0xf bank_mask:0xf bound_ctrl:1
	v_pk_fma_f32 v[220:221], v[146:147], v[212:213], v[220:221] op_sel_hi:[0,1,1] neg_lo:[1,0,0] neg_hi:[1,0,0]
	v_pk_fma_f32 v[222:223], v[146:147], v[214:215], v[222:223] op_sel_hi:[0,1,1] neg_lo:[1,0,0] neg_hi:[1,0,0]
	v_pk_fma_f32 v[138:139], v[138:139], v[216:217], v[220:221]
	v_pk_fma_f32 v[140:141], v[140:141], v[218:219], v[222:223]
	v_pk_mul_f32 v[144:145], v[138:139], v[230:231]
	v_pk_fma_f32 v[144:145], v[140:141], v[232:233], v[144:145]
	v_add_f32 v146, v144, v145
	ds_read_b128 v[186:189], v10 offset:44544
	ds_read_b128 v[190:193], v10 offset:44800
	ds_read_b128 v[194:197], v10 offset:45056
	ds_read_b128 v[198:201], v10 offset:45312
	ds_read_b128 v[202:205], v10 offset:45568
	ds_read_b32 v206, v11 offset:44544
	v_add_f32_dpp v146, v146, v146 quad_perm:[1,0,3,2] row_mask:0xf bank_mask:0xf bound_ctrl:1
	v_pk_mul_f32 v[224:225], v[138:139], v[224:225]
	v_pk_fma_f32 v[224:225], v[140:141], v[226:227], v[224:225]
	v_add_f32_dpp v146, v146, v146 quad_perm:[2,3,0,1] row_mask:0xf bank_mask:0xf bound_ctrl:1
	v_add_f32 v158, v224, v225
	v_pk_mul_f32 v[242:243], v[242:243], v[250:251] op_sel_hi:[1,0]
	v_add_f32_dpp v146, v146, v146 row_half_mirror row_mask:0xf bank_mask:0xf bound_ctrl:1
	v_pk_mul_f32 v[244:245], v[244:245], v[250:251] op_sel_hi:[1,0]
	s_waitcnt lgkmcnt(6)
	v_add_f32_dpp v146, v146, v146 row_mirror row_mask:0xf bank_mask:0xf bound_ctrl:1
	v_pk_fma_f32 v[242:243], v[146:147], v[234:235], v[242:243] op_sel_hi:[0,1,1] neg_lo:[1,0,0] neg_hi:[1,0,0]
	v_pk_fma_f32 v[244:245], v[146:147], v[236:237], v[244:245] op_sel_hi:[0,1,1] neg_lo:[1,0,0] neg_hi:[1,0,0]
	v_pk_fma_f32 v[138:139], v[138:139], v[238:239], v[242:243]
	v_pk_fma_f32 v[140:141], v[140:141], v[240:241], v[244:245]
	v_pk_mul_f32 v[144:145], v[138:139], v[164:165]
	v_pk_fma_f32 v[144:145], v[140:141], v[166:167], v[144:145]
	v_add_f32 v146, v144, v145
	ds_read_b128 v[208:211], v10 offset:46080
	ds_read_b128 v[212:215], v10 offset:46336
	ds_read_b128 v[216:219], v10 offset:46592
	ds_read_b128 v[220:223], v10 offset:46848
	ds_read_b128 v[224:227], v10 offset:47104
	ds_read_b32 v228, v11 offset:46080
	v_add_f32_dpp v146, v146, v146 quad_perm:[1,0,3,2] row_mask:0xf bank_mask:0xf bound_ctrl:1
	v_pk_mul_f32 v[246:247], v[138:139], v[246:247]
	v_pk_fma_f32 v[246:247], v[140:141], v[248:249], v[246:247]
	v_add_f32_dpp v146, v146, v146 quad_perm:[2,3,0,1] row_mask:0xf bank_mask:0xf bound_ctrl:1
	v_add_f32 v159, v246, v247
	v_pk_mul_f32 v[176:177], v[176:177], v[184:185] op_sel_hi:[1,0]
	v_add_f32_dpp v146, v146, v146 row_half_mirror row_mask:0xf bank_mask:0xf bound_ctrl:1
	v_pk_mul_f32 v[178:179], v[178:179], v[184:185] op_sel_hi:[1,0]
	s_waitcnt lgkmcnt(6)
	v_add_f32_dpp v146, v146, v146 row_mirror row_mask:0xf bank_mask:0xf bound_ctrl:1
	v_pk_fma_f32 v[176:177], v[146:147], v[168:169], v[176:177] op_sel_hi:[0,1,1] neg_lo:[1,0,0] neg_hi:[1,0,0]
	v_pk_fma_f32 v[178:179], v[146:147], v[170:171], v[178:179] op_sel_hi:[0,1,1] neg_lo:[1,0,0] neg_hi:[1,0,0]
	v_pk_fma_f32 v[138:139], v[138:139], v[172:173], v[176:177]
	v_pk_fma_f32 v[140:141], v[140:141], v[174:175], v[178:179]
	v_pk_mul_f32 v[144:145], v[138:139], v[186:187]
	v_pk_fma_f32 v[144:145], v[140:141], v[188:189], v[144:145]
	v_add_f32 v146, v144, v145
	ds_read_b128 v[230:233], v10 offset:47616
	ds_read_b128 v[234:237], v10 offset:47872
	ds_read_b128 v[238:241], v10 offset:48128
	ds_read_b128 v[242:245], v10 offset:48384
	ds_read_b128 v[246:249], v10 offset:48640
	ds_read_b32 v250, v11 offset:47616
	v_add_f32_dpp v146, v146, v146 quad_perm:[1,0,3,2] row_mask:0xf bank_mask:0xf bound_ctrl:1
	v_pk_mul_f32 v[180:181], v[138:139], v[180:181]
	v_pk_fma_f32 v[180:181], v[140:141], v[182:183], v[180:181]
	v_add_f32_dpp v146, v146, v146 quad_perm:[2,3,0,1] row_mask:0xf bank_mask:0xf bound_ctrl:1
	v_add_f32 v160, v180, v181
	v_pk_mul_f32 v[198:199], v[198:199], v[206:207] op_sel_hi:[1,0]
	v_add_f32_dpp v146, v146, v146 row_half_mirror row_mask:0xf bank_mask:0xf bound_ctrl:1
	v_pk_mul_f32 v[200:201], v[200:201], v[206:207] op_sel_hi:[1,0]
	s_waitcnt lgkmcnt(6)
	v_add_f32_dpp v146, v146, v146 row_mirror row_mask:0xf bank_mask:0xf bound_ctrl:1
	v_pk_fma_f32 v[198:199], v[146:147], v[190:191], v[198:199] op_sel_hi:[0,1,1] neg_lo:[1,0,0] neg_hi:[1,0,0]
	v_pk_fma_f32 v[200:201], v[146:147], v[192:193], v[200:201] op_sel_hi:[0,1,1] neg_lo:[1,0,0] neg_hi:[1,0,0]
	v_pk_fma_f32 v[138:139], v[138:139], v[194:195], v[198:199]
	v_pk_fma_f32 v[140:141], v[140:141], v[196:197], v[200:201]
	v_pk_mul_f32 v[144:145], v[138:139], v[208:209]
	v_pk_fma_f32 v[144:145], v[140:141], v[210:211], v[144:145]
	v_add_f32 v146, v144, v145
	s_nop 1
	v_add_f32_dpp v146, v146, v146 quad_perm:[1,0,3,2] row_mask:0xf bank_mask:0xf bound_ctrl:1
	v_pk_mul_f32 v[202:203], v[138:139], v[202:203]
	v_pk_fma_f32 v[202:203], v[140:141], v[204:205], v[202:203]
	v_add_f32_dpp v146, v146, v146 quad_perm:[2,3,0,1] row_mask:0xf bank_mask:0xf bound_ctrl:1
	v_add_f32 v161, v202, v203
	v_pk_mul_f32 v[220:221], v[220:221], v[228:229] op_sel_hi:[1,0]
	v_add_f32_dpp v146, v146, v146 row_half_mirror row_mask:0xf bank_mask:0xf bound_ctrl:1
	v_pk_mul_f32 v[222:223], v[222:223], v[228:229] op_sel_hi:[1,0]
	s_waitcnt lgkmcnt(0)
	v_add_f32_dpp v146, v146, v146 row_mirror row_mask:0xf bank_mask:0xf bound_ctrl:1
	v_pk_fma_f32 v[220:221], v[146:147], v[212:213], v[220:221] op_sel_hi:[0,1,1] neg_lo:[1,0,0] neg_hi:[1,0,0]
	v_pk_fma_f32 v[222:223], v[146:147], v[214:215], v[222:223] op_sel_hi:[0,1,1] neg_lo:[1,0,0] neg_hi:[1,0,0]
	v_pk_fma_f32 v[138:139], v[138:139], v[216:217], v[220:221]
	v_pk_fma_f32 v[140:141], v[140:141], v[218:219], v[222:223]
	v_pk_mul_f32 v[144:145], v[138:139], v[230:231]
	v_pk_fma_f32 v[144:145], v[140:141], v[232:233], v[144:145]
	v_add_f32 v146, v144, v145
	s_nop 1
	v_add_f32_dpp v146, v146, v146 quad_perm:[1,0,3,2] row_mask:0xf bank_mask:0xf bound_ctrl:1
	v_pk_mul_f32 v[224:225], v[138:139], v[224:225]
	v_pk_fma_f32 v[224:225], v[140:141], v[226:227], v[224:225]
	v_add_f32_dpp v146, v146, v146 quad_perm:[2,3,0,1] row_mask:0xf bank_mask:0xf bound_ctrl:1
	v_add_f32 v162, v224, v225
	v_pk_mul_f32 v[242:243], v[242:243], v[250:251] op_sel_hi:[1,0]
	v_add_f32_dpp v146, v146, v146 row_half_mirror row_mask:0xf bank_mask:0xf bound_ctrl:1
	v_pk_mul_f32 v[244:245], v[244:245], v[250:251] op_sel_hi:[1,0]
	s_nop 0
	v_add_f32_dpp v146, v146, v146 row_mirror row_mask:0xf bank_mask:0xf bound_ctrl:1
	v_pk_fma_f32 v[242:243], v[146:147], v[234:235], v[242:243] op_sel_hi:[0,1,1] neg_lo:[1,0,0] neg_hi:[1,0,0]
	v_pk_fma_f32 v[244:245], v[146:147], v[236:237], v[244:245] op_sel_hi:[0,1,1] neg_lo:[1,0,0] neg_hi:[1,0,0]
	v_pk_fma_f32 v[138:139], v[138:139], v[238:239], v[242:243]
	v_pk_fma_f32 v[140:141], v[140:141], v[240:241], v[244:245]
	v_pk_mul_f32 v[246:247], v[138:139], v[246:247]
	v_pk_fma_f32 v[246:247], v[140:141], v[248:249], v[246:247]
	v_add_f32 v163, v246, v247
	s_nop 0
	v_add_f32_dpp v230, v148, v148 row_mirror row_mask:0xf bank_mask:0x3 bound_ctrl:1
	v_add_f32_dpp v230, v156, v156 row_mirror row_mask:0xf bank_mask:0xc bound_ctrl:1
	v_add_f32_dpp v231, v149, v149 row_mirror row_mask:0xf bank_mask:0x3 bound_ctrl:1
	v_add_f32_dpp v231, v157, v157 row_mirror row_mask:0xf bank_mask:0xc bound_ctrl:1
	v_add_f32_dpp v232, v150, v150 row_mirror row_mask:0xf bank_mask:0x3 bound_ctrl:1
	v_add_f32_dpp v232, v158, v158 row_mirror row_mask:0xf bank_mask:0xc bound_ctrl:1
	v_add_f32_dpp v233, v151, v151 row_mirror row_mask:0xf bank_mask:0x3 bound_ctrl:1
	v_add_f32_dpp v233, v159, v159 row_mirror row_mask:0xf bank_mask:0xc bound_ctrl:1
	v_add_f32_dpp v234, v152, v152 row_mirror row_mask:0xf bank_mask:0x3 bound_ctrl:1
	v_add_f32_dpp v234, v160, v160 row_mirror row_mask:0xf bank_mask:0xc bound_ctrl:1
	v_add_f32_dpp v235, v153, v153 row_mirror row_mask:0xf bank_mask:0x3 bound_ctrl:1
	v_add_f32_dpp v235, v161, v161 row_mirror row_mask:0xf bank_mask:0xc bound_ctrl:1
	v_add_f32_dpp v236, v154, v154 row_mirror row_mask:0xf bank_mask:0x3 bound_ctrl:1
	v_add_f32_dpp v236, v162, v162 row_mirror row_mask:0xf bank_mask:0xc bound_ctrl:1
	v_add_f32_dpp v237, v155, v155 row_mirror row_mask:0xf bank_mask:0x3 bound_ctrl:1
	v_add_f32_dpp v237, v163, v163 row_mirror row_mask:0xf bank_mask:0xc bound_ctrl:1
	v_add_f32_dpp v238, v230, v230 row_half_mirror row_mask:0xf bank_mask:0x5 bound_ctrl:1
	v_add_f32_dpp v238, v234, v234 row_half_mirror row_mask:0xf bank_mask:0xa bound_ctrl:1
	v_add_f32_dpp v239, v231, v231 row_half_mirror row_mask:0xf bank_mask:0x5 bound_ctrl:1
	v_add_f32_dpp v239, v235, v235 row_half_mirror row_mask:0xf bank_mask:0xa bound_ctrl:1
	v_add_f32_dpp v240, v232, v232 row_half_mirror row_mask:0xf bank_mask:0x5 bound_ctrl:1
	v_add_f32_dpp v240, v236, v236 row_half_mirror row_mask:0xf bank_mask:0xa bound_ctrl:1
	v_add_f32_dpp v241, v233, v233 row_half_mirror row_mask:0xf bank_mask:0x5 bound_ctrl:1
	v_add_f32_dpp v241, v237, v237 row_half_mirror row_mask:0xf bank_mask:0xa bound_ctrl:1
	s_mov_b32 vcc_lo, 0xcccccccc
	s_mov_b32 vcc_hi, 0xcccccccc
	v_cndmask_b32 v244, v240, v238, vcc
	v_cndmask_b32 v245, v241, v239, vcc
	v_cndmask_b32 v242, v238, v240, vcc
	v_cndmask_b32 v243, v239, v241, vcc
	v_add_f32_dpp v242, v244, v242 quad_perm:[2,3,0,1] row_mask:0xf bank_mask:0xf bound_ctrl:1
	v_add_f32_dpp v243, v245, v243 quad_perm:[2,3,0,1] row_mask:0xf bank_mask:0xf bound_ctrl:1
	s_mov_b32 vcc_lo, 0xaaaaaaaa
	s_mov_b32 vcc_hi, 0xaaaaaaaa
	v_cndmask_b32 v244, v243, v242, vcc
	v_cndmask_b32 v245, v242, v243, vcc
	s_nop 0
	v_add_f32_dpp v19, v244, v245 quad_perm:[1,0,3,2] row_mask:0xf bank_mask:0xf bound_ctrl:1

; #define SCAN_BAR() asm volatile("s_barrier" ::: "memory")
; __device__ __forceinline__ void scan_unit(const Ctx& C0, const float* scn, int T, int quarter, const float* S0, float* Sout, unsigned char* obase, int mode) {
;     ...
;             if (mode == 0) { *(float*)(obase + (size_t)(k * 32 + q) * UPITCH_B + rl * 4) = osel0; *(float*)(obase + (size_t)(k * 32 + 16 + q) * UPITCH_B + rl * 4) = osel1; }
;             SCAN_BAR();
;         }
;         if (mode == 0) *(f32x4*)(Sout + irow * 64 + 4 * q) = (f32x4){S0x, S1x, S2x, S3x};
	s_addc_u32 s1, s1, 0
	v_add_co_u32_e32 v16, vcc, s8, v14
	s_cmp_lg_u32 s0, 0x5600000
	s_nop 0
	v_addc_co_u32_e32 v17, vcc, 0, v15, vcc
	v_add_co_u32_e32 v14, vcc, 0xfcaa000, v14
	global_store_dword v[16:17], v18, off offset:768
	s_nop 0
	v_addc_co_u32_e32 v15, vcc, 0, v15, vcc
	global_store_dword v[14:15], v19, off offset:768
	s_barrier
	s_cbranch_scc1 .LBB0_685
	s_setprio 0
	v_mov_b32_e32 v2, v138
	v_mov_b32_e32 v13, v139
	v_mov_b32_e32 v12, v140
	v_mov_b32_e32 v8, v141
	v_readlane_b32 s0, v255, 46
	s_add_i32 s0, s3, s0
	s_ashr_i32 s1, s0, 31
	s_lshl_b64 s[0:1], s[0:1], 17
	v_readlane_b32 s3, v253, 26
	s_add_u32 s0, s3, s0
	v_readlane_b32 s3, v253, 27
	s_addc_u32 s1, s3, s1
	s_lshl_b32 s2, s2, 14
	s_add_u32 s0, s0, s2
	s_addc_u32 s1, s1, 0
	v_lshlrev_b32_e32 v0, 8, v0
	v_lshl_add_u64 v[6:7], s[0:1], 0, v[0:1]
	v_mov_b32_e32 v5, v1
	v_lshl_add_u64 v[6:7], v[6:7], 0, v[4:5]
	v_mov_b32_e32 v3, v13
	v_mov_b32_e32 v4, v12
	v_mov_b32_e32 v5, v8
	global_store_dwordx4 v[6:7], v[2:5], off
